# v11 + SwiGLU epilogue: one v_rcp_f32 of a 4-product (or 2-product) instead of one per element, inverses recovered by packed multiplies (fewer transcendental issues)
# baseline (speedup 1.0000x reference)
; __device__ __forceinline__ unsigned cvt_pk_bf16(float lo, float hi) { unsigned r; asm volatile("v_cvt_pk_bf16_f32 %0, %1, %2" : "=v"(r) : "v"(lo), "v"(hi)); return r; }
; __device__ __forceinline__ float ss_val(u64 v) { return (float)v * (1.0f / 1099511627776.0f); }
;     __device__ __forceinline__ void operator()(const f32x4 (&acc)[2][2][4][2], const Unit& u, const Unit& nxt, bool has_next, int wr, int wc, int fr, int fq) const {
;     ...
;         for (int g = 0; g < 8; ++g) {
;             const int ai = g >> 2, m = g & 3;
;             const float rs = __builtin_amdgcn_rsqf(ss_val(cur[g]) * inv_k + eps), rsn = rs * -1.44269504089f, rs2 = rs * rs;
;             float h[8];
; #pragma unroll
;             for (int n = 0; n < 2; ++n)
; #pragma unroll
;                 for (int jp = 0; jp < 2; ++jp) {
;                     const f32x2v av = {acc[ai][0][m][n][2 * jp], acc[ai][0][m][n][2 * jp + 1]}, gv = {acc[ai][1][m][n][2 * jp], acc[ai][1][m][n][2 * jp + 1]};
;                     const f32x2v t = (av * gv) * rs2, y = gv * rsn;
;                     f32x2v ex; ex.x = __builtin_amdgcn_exp2f(y.x); ex.y = __builtin_amdgcn_exp2f(y.y);
;                     const f32x2v d = ex + 1.0f;
;                     f32x2v r; r.x = __builtin_amdgcn_rcpf(d.x); r.y = __builtin_amdgcn_rcpf(d.y);
;                     const f32x2v o = t * r;
;                     h[4 * n + 2 * jp] = o.x; h[4 * n + 2 * jp + 1] = o.y;
;                 }
;             u32x4 w; w.x = cvt_pk_bf16(h[0], h[1]); w.y = cvt_pk_bf16(h[2], h[3]); w.z = cvt_pk_bf16(h[4], h[5]); w.w = cvt_pk_bf16(h[6], h[7]);
;             *(u32x4*)(O + (size_t)(row0 + ai * HALF + m * 16) * ldc + col0) = w;
;         }
.LBB0_180:
	s_waitcnt vmcnt(0)
	v_or_b32_e32 v185, 16, v168
	v_pk_mul_f32 v[124:125], v[124:125], v[116:117]
	v_cvt_f32_u32_e32 v172, v172
	v_cvt_f32_u32_e32 v173, v173
	v_fmamk_f32 v172, v173, 0x4f800000, v172
	v_fmamk_f32 v169, v172, 0x26800000, v180
	v_mov_b32_e32 v232, v169
	v_rsq_f32_e32 v186, v169
	v_pk_mul_f32 v[120:121], v[120:121], v[112:113]
	v_pk_mul_f32 v[126:127], v[126:127], v[118:119]
	v_pk_mul_f32 v[122:123], v[122:123], v[114:115]
	v_mul_f32_e32 v184, 0xbfb8aa3b, v186
	v_pk_mul_f32 v[116:117], v[116:117], v[184:185] op_sel_hi:[1,0]
	v_pk_mul_f32 v[112:113], v[112:113], v[184:185] op_sel_hi:[1,0]
	v_exp_f32_e32 v116, v116
	v_exp_f32_e32 v117, v117
	v_pk_mul_f32 v[118:119], v[118:119], v[184:185] op_sel_hi:[1,0]
	v_exp_f32_e32 v112, v112
	v_exp_f32_e32 v113, v113
	v_pk_mul_f32 v[114:115], v[114:115], v[184:185] op_sel_hi:[1,0]
	v_exp_f32_e32 v118, v118
	v_exp_f32_e32 v119, v119
	v_exp_f32_e32 v114, v114
	v_exp_f32_e32 v115, v115
	v_pk_fma_f32 v[116:117], v[116:117], v[232:233], v[232:233] op_sel_hi:[1,0,0]
	v_pk_fma_f32 v[112:113], v[112:113], v[232:233], v[232:233] op_sel_hi:[1,0,0]
	v_pk_fma_f32 v[118:119], v[118:119], v[232:233], v[232:233] op_sel_hi:[1,0,0]
	v_pk_mul_f32 v[248:249], v[116:117], v[112:113]
	v_mul_f32_e32 v250, v248, v249
	v_rcp_f32_e32 v250, v250
	s_nop 0
	v_pk_mul_f32 v[248:249], v[248:249], v[250:251] op_sel:[1,0] op_sel_hi:[0,0]
	v_pk_mul_f32 v[252:253], v[248:249], v[116:117]
	v_pk_mul_f32 v[116:117], v[248:249], v[112:113]
	v_pk_fma_f32 v[114:115], v[114:115], v[232:233], v[232:233] op_sel_hi:[1,0,0]
	v_pk_mul_f32 v[248:249], v[118:119], v[114:115]
	v_mul_f32_e32 v250, v248, v249
	v_rcp_f32_e32 v250, v250
	s_nop 0
	v_pk_mul_f32 v[248:249], v[248:249], v[250:251] op_sel:[1,0] op_sel_hi:[0,0]
	v_pk_mul_f32 v[254:255], v[248:249], v[118:119]
	v_pk_mul_f32 v[118:119], v[248:249], v[114:115]
	v_or_b32_e32 v187, 32, v168
	v_pk_mul_f32 v[116:117], v[124:125], v[116:117]
	v_pk_mul_f32 v[112:113], v[120:121], v[252:253]
	v_pk_mul_f32 v[118:119], v[126:127], v[118:119]
	v_pk_mul_f32 v[114:115], v[122:123], v[254:255]
	v_cvt_pk_bf16_f32 v116, v116, v117
	v_cvt_pk_bf16_f32 v117, v118, v119
	v_cvt_pk_bf16_f32 v118, v112, v113
	v_lshl_or_b32 v182, s70, 7, v176
	v_cvt_pk_bf16_f32 v119, v114, v115
	v_ashrrev_i32_e32 v183, 31, v182
	v_mov_b64_e32 v[112:113], s[24:25]
	v_cvt_f32_u32_e32 v170, v170
	v_cvt_f32_u32_e32 v171, v171
	v_fmamk_f32 v170, v171, 0x4f800000, v170
	v_fmamk_f32 v114, v170, 0x26800000, v180
	v_mov_b32_e32 v234, v114
	v_rsq_f32_e32 v122, v114
	v_mad_i64_i32 v[120:121], s[56:57], v168, s69, v[112:113]
	v_lshlrev_b64 v[114:115], 1, v[182:183]
	v_lshl_add_u64 v[120:121], v[120:121], 0, v[114:115]
	global_store_dwordx4 v[120:121], v[116:119], off
	v_pk_mul_f32 v[104:105], v[104:105], v[96:97]
	v_pk_mul_f32 v[108:109], v[108:109], v[100:101]
	v_mul_f32_e32 v116, 0xbfb8aa3b, v122
	v_pk_mul_f32 v[96:97], v[96:97], v[116:117] op_sel_hi:[1,0]
	v_pk_mul_f32 v[100:101], v[100:101], v[116:117] op_sel_hi:[1,0]
	v_pk_mul_f32 v[106:107], v[106:107], v[98:99]
	v_exp_f32_e32 v96, v96
	v_exp_f32_e32 v97, v97
	v_pk_mul_f32 v[98:99], v[98:99], v[116:117] op_sel_hi:[1,0]
	v_exp_f32_e32 v100, v100
	v_exp_f32_e32 v101, v101
	v_exp_f32_e32 v98, v98
	v_exp_f32_e32 v99, v99
	v_pk_fma_f32 v[96:97], v[96:97], v[234:235], v[234:235] op_sel_hi:[1,0,0]
	v_pk_fma_f32 v[100:101], v[100:101], v[234:235], v[234:235] op_sel_hi:[1,0,0]
	v_pk_fma_f32 v[98:99], v[98:99], v[234:235], v[234:235] op_sel_hi:[1,0,0]
	v_pk_mul_f32 v[248:249], v[96:97], v[100:101]
	v_mul_f32_e32 v250, v248, v249
	v_rcp_f32_e32 v250, v250
	s_nop 0
	v_pk_mul_f32 v[248:249], v[248:249], v[250:251] op_sel:[1,0] op_sel_hi:[0,0]
	v_pk_mul_f32 v[252:253], v[248:249], v[96:97]
	v_pk_mul_f32 v[96:97], v[248:249], v[100:101]
	v_mul_f32_e32 v250, v98, v99
	v_rcp_f32_e32 v250, v250
	s_nop 0
	v_pk_mul_f32 v[98:99], v[98:99], v[250:251] op_sel:[1,0] op_sel_hi:[0,0]
	v_pk_mul_f32 v[104:105], v[104:105], v[96:97]
	v_pk_mul_f32 v[100:101], v[108:109], v[252:253]
	v_pk_mul_f32 v[106:107], v[106:107], v[98:99]
	v_pk_mul_f32 v[110:111], v[110:111], v[102:103]
	v_pk_mul_f32 v[102:103], v[102:103], v[116:117] op_sel_hi:[1,0]
	v_cvt_pk_bf16_f32 v96, v100, v101
	v_exp_f32_e32 v102, v102
	v_exp_f32_e32 v103, v103
	s_nop 0
	v_pk_fma_f32 v[102:103], v[102:103], v[234:235], v[234:235] op_sel_hi:[1,0,0]
	v_mul_f32_e32 v250, v102, v103
	v_rcp_f32_e32 v250, v250
	s_nop 0
	v_pk_mul_f32 v[102:103], v[102:103], v[250:251] op_sel:[1,0] op_sel_hi:[0,0]
	s_nop 0
	v_pk_mul_f32 v[102:103], v[110:111], v[102:103]
	v_cvt_f32_u32_e32 v166, v166
	v_cvt_f32_u32_e32 v167, v167
	v_fmamk_f32 v166, v167, 0x4f800000, v166
	v_fmamk_f32 v100, v166, 0x26800000, v180
	v_mov_b32_e32 v236, v100
	v_cvt_pk_bf16_f32 v97, v102, v103
	v_rsq_f32_e32 v102, v100
	v_mad_i64_i32 v[100:101], s[56:57], v185, s69, v[112:113]
	v_lshl_add_u64 v[100:101], v[100:101], 0, v[114:115]
	v_cvt_pk_bf16_f32 v98, v104, v105
	v_cvt_pk_bf16_f32 v99, v106, v107
	global_store_dwordx4 v[100:101], v[96:99], off
	v_pk_mul_f32 v[88:89], v[88:89], v[80:81]
	v_pk_mul_f32 v[92:93], v[92:93], v[84:85]
	v_mul_f32_e32 v96, 0xbfb8aa3b, v102
	v_pk_mul_f32 v[80:81], v[80:81], v[96:97] op_sel_hi:[1,0]
	v_pk_mul_f32 v[84:85], v[84:85], v[96:97] op_sel_hi:[1,0]
	v_pk_mul_f32 v[90:91], v[90:91], v[82:83]
	v_exp_f32_e32 v80, v80
	v_exp_f32_e32 v81, v81
	v_pk_mul_f32 v[82:83], v[82:83], v[96:97] op_sel_hi:[1,0]
	v_exp_f32_e32 v84, v84
	v_exp_f32_e32 v85, v85
	v_exp_f32_e32 v82, v82
	v_exp_f32_e32 v83, v83
	v_pk_fma_f32 v[80:81], v[80:81], v[236:237], v[236:237] op_sel_hi:[1,0,0]
	v_pk_fma_f32 v[84:85], v[84:85], v[236:237], v[236:237] op_sel_hi:[1,0,0]
; __device__ __forceinline__ unsigned cvt_pk_bf16(float lo, float hi) { unsigned r; asm volatile("v_cvt_pk_bf16_f32 %0, %1, %2" : "=v"(r) : "v"(lo), "v"(hi)); return r; }
; __device__ __forceinline__ float ss_val(u64 v) { return (float)v * (1.0f / 1099511627776.0f); }
;     __device__ __forceinline__ void operator()(const f32x4 (&acc)[2][2][4][2], const Unit& u, const Unit& nxt, bool has_next, int wr, int wc, int fr, int fq) const {
;     ...
;         for (int g = 0; g < 8; ++g) {
;             const int ai = g >> 2, m = g & 3;
;             const float rs = __builtin_amdgcn_rsqf(ss_val(cur[g]) * inv_k + eps), rsn = rs * -1.44269504089f, rs2 = rs * rs;
;             float h[8];
; #pragma unroll
;             for (int n = 0; n < 2; ++n)
; #pragma unroll
;                 for (int jp = 0; jp < 2; ++jp) {
;                     const f32x2v av = {acc[ai][0][m][n][2 * jp], acc[ai][0][m][n][2 * jp + 1]}, gv = {acc[ai][1][m][n][2 * jp], acc[ai][1][m][n][2 * jp + 1]};
;                     const f32x2v t = (av * gv) * rs2, y = gv * rsn;
;                     f32x2v ex; ex.x = __builtin_amdgcn_exp2f(y.x); ex.y = __builtin_amdgcn_exp2f(y.y);
;                     const f32x2v d = ex + 1.0f;
;                     f32x2v r; r.x = __builtin_amdgcn_rcpf(d.x); r.y = __builtin_amdgcn_rcpf(d.y);
;                     const f32x2v o = t * r;
;                     h[4 * n + 2 * jp] = o.x; h[4 * n + 2 * jp + 1] = o.y;
;                 }
;             u32x4 w; w.x = cvt_pk_bf16(h[0], h[1]); w.y = cvt_pk_bf16(h[2], h[3]); w.z = cvt_pk_bf16(h[4], h[5]); w.w = cvt_pk_bf16(h[6], h[7]);
;             *(u32x4*)(O + (size_t)(row0 + ai * HALF + m * 16) * ldc + col0) = w;
;         }
	v_pk_fma_f32 v[82:83], v[82:83], v[236:237], v[236:237] op_sel_hi:[1,0,0]
	v_pk_mul_f32 v[248:249], v[80:81], v[84:85]
	v_mul_f32_e32 v250, v248, v249
	v_rcp_f32_e32 v250, v250
	s_nop 0
	v_pk_mul_f32 v[248:249], v[248:249], v[250:251] op_sel:[1,0] op_sel_hi:[0,0]
	v_pk_mul_f32 v[252:253], v[248:249], v[80:81]
	v_pk_mul_f32 v[80:81], v[248:249], v[84:85]
	v_mul_f32_e32 v250, v82, v83
	v_rcp_f32_e32 v250, v250
	s_nop 0
	v_pk_mul_f32 v[82:83], v[82:83], v[250:251] op_sel:[1,0] op_sel_hi:[0,0]
	v_pk_mul_f32 v[88:89], v[88:89], v[80:81]
	v_pk_mul_f32 v[84:85], v[92:93], v[252:253]
	v_pk_mul_f32 v[90:91], v[90:91], v[82:83]
	v_pk_mul_f32 v[94:95], v[94:95], v[86:87]
	v_pk_mul_f32 v[86:87], v[86:87], v[96:97] op_sel_hi:[1,0]
	v_cvt_pk_bf16_f32 v80, v84, v85
	v_exp_f32_e32 v86, v86
	v_exp_f32_e32 v87, v87
	s_nop 0
	v_pk_fma_f32 v[86:87], v[86:87], v[236:237], v[236:237] op_sel_hi:[1,0,0]
	v_mul_f32_e32 v250, v86, v87
	v_rcp_f32_e32 v250, v250
	s_nop 0
	v_pk_mul_f32 v[86:87], v[86:87], v[250:251] op_sel:[1,0] op_sel_hi:[0,0]
	s_nop 0
	v_pk_mul_f32 v[86:87], v[94:95], v[86:87]
	v_cvt_f32_u32_e32 v164, v164
	v_cvt_f32_u32_e32 v165, v165
	v_fmamk_f32 v164, v165, 0x4f800000, v164
	v_fmamk_f32 v84, v164, 0x26800000, v180
	v_mov_b32_e32 v238, v84
	v_cvt_pk_bf16_f32 v81, v86, v87
	v_rsq_f32_e32 v86, v84
	v_mad_i64_i32 v[84:85], s[56:57], v187, s69, v[112:113]
	v_lshl_add_u64 v[84:85], v[84:85], 0, v[114:115]
	v_cvt_pk_bf16_f32 v82, v88, v89
	v_cvt_pk_bf16_f32 v83, v90, v91
	global_store_dwordx4 v[84:85], v[80:83], off
	v_pk_mul_f32 v[72:73], v[72:73], v[64:65]
	v_pk_mul_f32 v[76:77], v[76:77], v[68:69]
	v_mul_f32_e32 v80, 0xbfb8aa3b, v86
	v_pk_mul_f32 v[64:65], v[64:65], v[80:81] op_sel_hi:[1,0]
	v_pk_mul_f32 v[68:69], v[68:69], v[80:81] op_sel_hi:[1,0]
	v_pk_mul_f32 v[74:75], v[74:75], v[66:67]
	v_exp_f32_e32 v64, v64
	v_exp_f32_e32 v65, v65
	v_pk_mul_f32 v[66:67], v[66:67], v[80:81] op_sel_hi:[1,0]
	v_exp_f32_e32 v68, v68
	v_exp_f32_e32 v69, v69
	v_exp_f32_e32 v66, v66
	v_exp_f32_e32 v67, v67
	v_pk_fma_f32 v[64:65], v[64:65], v[238:239], v[238:239] op_sel_hi:[1,0,0]
	v_pk_fma_f32 v[68:69], v[68:69], v[238:239], v[238:239] op_sel_hi:[1,0,0]
	v_pk_fma_f32 v[66:67], v[66:67], v[238:239], v[238:239] op_sel_hi:[1,0,0]
	v_pk_mul_f32 v[248:249], v[64:65], v[68:69]
	v_mul_f32_e32 v250, v248, v249
	v_rcp_f32_e32 v250, v250
	s_nop 0
	v_pk_mul_f32 v[248:249], v[248:249], v[250:251] op_sel:[1,0] op_sel_hi:[0,0]
	v_pk_mul_f32 v[252:253], v[248:249], v[64:65]
	v_pk_mul_f32 v[64:65], v[248:249], v[68:69]
	v_mul_f32_e32 v250, v66, v67
	v_rcp_f32_e32 v250, v250
	s_nop 0
	v_pk_mul_f32 v[66:67], v[66:67], v[250:251] op_sel:[1,0] op_sel_hi:[0,0]
	v_pk_mul_f32 v[72:73], v[72:73], v[64:65]
	v_pk_mul_f32 v[68:69], v[76:77], v[252:253]
	v_pk_mul_f32 v[74:75], v[74:75], v[66:67]
	v_pk_mul_f32 v[78:79], v[78:79], v[70:71]
	v_pk_mul_f32 v[70:71], v[70:71], v[80:81] op_sel_hi:[1,0]
	v_cvt_pk_bf16_f32 v64, v68, v69
	v_exp_f32_e32 v70, v70
	v_exp_f32_e32 v71, v71
	s_nop 0
	v_pk_fma_f32 v[70:71], v[70:71], v[238:239], v[238:239] op_sel_hi:[1,0,0]
	v_mul_f32_e32 v250, v70, v71
	v_rcp_f32_e32 v250, v250
	s_nop 0
	v_pk_mul_f32 v[70:71], v[70:71], v[250:251] op_sel:[1,0] op_sel_hi:[0,0]
	s_nop 0
	v_pk_mul_f32 v[70:71], v[78:79], v[70:71]
	v_cvt_f32_u32_e32 v162, v162
	v_cvt_f32_u32_e32 v163, v163
	v_fmamk_f32 v162, v163, 0x4f800000, v162
	v_fmamk_f32 v68, v162, 0x26800000, v180
	v_mov_b32_e32 v240, v68
	v_cvt_pk_bf16_f32 v65, v70, v71
	v_rsq_f32_e32 v70, v68
	v_or_b32_e32 v188, 48, v168
	v_mad_i64_i32 v[68:69], s[56:57], v188, s69, v[112:113]
	v_lshl_add_u64 v[68:69], v[68:69], 0, v[114:115]
	v_cvt_pk_bf16_f32 v66, v72, v73
	v_cvt_pk_bf16_f32 v67, v74, v75
	global_store_dwordx4 v[68:69], v[64:67], off
	v_pk_mul_f32 v[56:57], v[56:57], v[48:49]
	v_pk_mul_f32 v[60:61], v[60:61], v[52:53]
	v_mul_f32_e32 v64, 0xbfb8aa3b, v70
	v_pk_mul_f32 v[48:49], v[48:49], v[64:65] op_sel_hi:[1,0]
	v_pk_mul_f32 v[52:53], v[52:53], v[64:65] op_sel_hi:[1,0]
	v_pk_mul_f32 v[58:59], v[58:59], v[50:51]
	v_exp_f32_e32 v48, v48
	v_exp_f32_e32 v49, v49
	v_pk_mul_f32 v[50:51], v[50:51], v[64:65] op_sel_hi:[1,0]
	v_exp_f32_e32 v52, v52
	v_exp_f32_e32 v53, v53
	v_exp_f32_e32 v50, v50
	v_exp_f32_e32 v51, v51
	v_pk_fma_f32 v[48:49], v[48:49], v[240:241], v[240:241] op_sel_hi:[1,0,0]
	v_pk_fma_f32 v[52:53], v[52:53], v[240:241], v[240:241] op_sel_hi:[1,0,0]
	v_pk_fma_f32 v[50:51], v[50:51], v[240:241], v[240:241] op_sel_hi:[1,0,0]
	v_pk_mul_f32 v[248:249], v[48:49], v[52:53]
	v_mul_f32_e32 v250, v248, v249
	v_rcp_f32_e32 v250, v250
	s_nop 0
	v_pk_mul_f32 v[248:249], v[248:249], v[250:251] op_sel:[1,0] op_sel_hi:[0,0]
	v_pk_mul_f32 v[252:253], v[248:249], v[48:49]
	v_pk_mul_f32 v[48:49], v[248:249], v[52:53]
	v_mul_f32_e32 v250, v50, v51
	v_rcp_f32_e32 v250, v250
	s_nop 0
	v_pk_mul_f32 v[50:51], v[50:51], v[250:251] op_sel:[1,0] op_sel_hi:[0,0]
	v_pk_mul_f32 v[56:57], v[56:57], v[48:49]
	v_pk_mul_f32 v[52:53], v[60:61], v[252:253]
	v_pk_mul_f32 v[58:59], v[58:59], v[50:51]
	v_pk_mul_f32 v[62:63], v[62:63], v[54:55]
	v_pk_mul_f32 v[54:55], v[54:55], v[64:65] op_sel_hi:[1,0]
	v_cvt_pk_bf16_f32 v48, v52, v53
	v_exp_f32_e32 v54, v54
	v_exp_f32_e32 v55, v55
	s_nop 0
	v_pk_fma_f32 v[54:55], v[54:55], v[240:241], v[240:241] op_sel_hi:[1,0,0]
	v_mul_f32_e32 v250, v54, v55
	v_rcp_f32_e32 v250, v250
	s_nop 0
	v_pk_mul_f32 v[54:55], v[54:55], v[250:251] op_sel:[1,0] op_sel_hi:[0,0]
	s_nop 0
	v_pk_mul_f32 v[54:55], v[62:63], v[54:55]
	v_cvt_f32_u32_e32 v160, v160
	v_cvt_f32_u32_e32 v161, v161
	v_fmamk_f32 v160, v161, 0x4f800000, v160
	v_fmamk_f32 v52, v160, 0x26800000, v180
	v_mov_b32_e32 v242, v52
	v_cvt_pk_bf16_f32 v49, v54, v55
; __device__ __forceinline__ unsigned cvt_pk_bf16(float lo, float hi) { unsigned r; asm volatile("v_cvt_pk_bf16_f32 %0, %1, %2" : "=v"(r) : "v"(lo), "v"(hi)); return r; }
; __device__ __forceinline__ float ss_val(u64 v) { return (float)v * (1.0f / 1099511627776.0f); }
; #define PG8_BAR __builtin_amdgcn_s_barrier()
;     __device__ __forceinline__ void operator()(const f32x4 (&acc)[2][2][4][2], const Unit& u, const Unit& nxt, bool has_next, int wr, int wc, int fr, int fq) const {
;     ...
;         for (int g = 0; g < 8; ++g) {
;             const int ai = g >> 2, m = g & 3;
;             const float rs = __builtin_amdgcn_rsqf(ss_val(cur[g]) * inv_k + eps), rsn = rs * -1.44269504089f, rs2 = rs * rs;
;             float h[8];
; #pragma unroll
;             for (int n = 0; n < 2; ++n)
; #pragma unroll
;                 for (int jp = 0; jp < 2; ++jp) {
;                     const f32x2v av = {acc[ai][0][m][n][2 * jp], acc[ai][0][m][n][2 * jp + 1]}, gv = {acc[ai][1][m][n][2 * jp], acc[ai][1][m][n][2 * jp + 1]};
;                     const f32x2v t = (av * gv) * rs2, y = gv * rsn;
;                     f32x2v ex; ex.x = __builtin_amdgcn_exp2f(y.x); ex.y = __builtin_amdgcn_exp2f(y.y);
;                     const f32x2v d = ex + 1.0f;
;                     f32x2v r; r.x = __builtin_amdgcn_rcpf(d.x); r.y = __builtin_amdgcn_rcpf(d.y);
;                     const f32x2v o = t * r;
;                     h[4 * n + 2 * jp] = o.x; h[4 * n + 2 * jp + 1] = o.y;
;                 }
;             u32x4 w; w.x = cvt_pk_bf16(h[0], h[1]); w.y = cvt_pk_bf16(h[2], h[3]); w.z = cvt_pk_bf16(h[4], h[5]); w.w = cvt_pk_bf16(h[6], h[7]);
;             *(u32x4*)(O + (size_t)(row0 + ai * HALF + m * 16) * ldc + col0) = w;
;         }
;         if (has_next) { u64 x = 0;
; #pragma unroll
;             for (int g = 0; g < 8; ++g) x |= warm[g];
;             asm volatile("" :: "v"((unsigned)x), "v"((unsigned)(x >> 32))); }
; template <class Epi, class Sched, bool ALIGN_EPI = false, bool SP2 = false>
; __device__ __forceinline__ void gemm_phase(PG8_LAS unsigned char* lds, const Gemm g, const Sched& S, const Epi& E) {
;     ...
;         cur = nxt; cA = nA; cB = nB; ++ui;
;         if constexpr (ALIGN_EPI) { if (wr == 1) PG8_BAR; }
	v_rsq_f32_e32 v54, v52
	v_add_u32_e32 v181, 0x80, v168
	v_mad_i64_i32 v[52:53], s[56:57], v181, s69, v[112:113]
	v_lshl_add_u64 v[52:53], v[52:53], 0, v[114:115]
	v_cvt_pk_bf16_f32 v50, v56, v57
	v_cvt_pk_bf16_f32 v51, v58, v59
	global_store_dwordx4 v[52:53], v[48:51], off
	v_pk_mul_f32 v[40:41], v[40:41], v[32:33]
	v_pk_mul_f32 v[44:45], v[44:45], v[36:37]
	v_mul_f32_e32 v48, 0xbfb8aa3b, v54
	v_pk_mul_f32 v[32:33], v[32:33], v[48:49] op_sel_hi:[1,0]
	v_pk_mul_f32 v[36:37], v[36:37], v[48:49] op_sel_hi:[1,0]
	v_pk_mul_f32 v[42:43], v[42:43], v[34:35]
	v_exp_f32_e32 v32, v32
	v_exp_f32_e32 v33, v33
	v_pk_mul_f32 v[34:35], v[34:35], v[48:49] op_sel_hi:[1,0]
	v_exp_f32_e32 v36, v36
	v_exp_f32_e32 v37, v37
	v_exp_f32_e32 v34, v34
	v_exp_f32_e32 v35, v35
	v_pk_fma_f32 v[32:33], v[32:33], v[242:243], v[242:243] op_sel_hi:[1,0,0]
	v_pk_fma_f32 v[36:37], v[36:37], v[242:243], v[242:243] op_sel_hi:[1,0,0]
	v_pk_fma_f32 v[34:35], v[34:35], v[242:243], v[242:243] op_sel_hi:[1,0,0]
	v_pk_mul_f32 v[248:249], v[32:33], v[36:37]
	v_mul_f32_e32 v250, v248, v249
	v_rcp_f32_e32 v250, v250
	s_nop 0
	v_pk_mul_f32 v[248:249], v[248:249], v[250:251] op_sel:[1,0] op_sel_hi:[0,0]
	v_pk_mul_f32 v[252:253], v[248:249], v[32:33]
	v_pk_mul_f32 v[32:33], v[248:249], v[36:37]
	v_mul_f32_e32 v250, v34, v35
	v_rcp_f32_e32 v250, v250
	s_nop 0
	v_pk_mul_f32 v[34:35], v[34:35], v[250:251] op_sel:[1,0] op_sel_hi:[0,0]
	v_pk_mul_f32 v[40:41], v[40:41], v[32:33]
	v_pk_mul_f32 v[36:37], v[44:45], v[252:253]
	v_pk_mul_f32 v[42:43], v[42:43], v[34:35]
	v_pk_mul_f32 v[46:47], v[46:47], v[38:39]
	v_pk_mul_f32 v[38:39], v[38:39], v[48:49] op_sel_hi:[1,0]
	v_cvt_pk_bf16_f32 v32, v36, v37
	v_exp_f32_e32 v38, v38
	v_exp_f32_e32 v39, v39
	s_nop 0
	v_pk_fma_f32 v[38:39], v[38:39], v[242:243], v[242:243] op_sel_hi:[1,0,0]
	v_mul_f32_e32 v250, v38, v39
	v_rcp_f32_e32 v250, v250
	s_nop 0
	v_pk_mul_f32 v[38:39], v[38:39], v[250:251] op_sel:[1,0] op_sel_hi:[0,0]
	s_nop 0
	v_pk_mul_f32 v[38:39], v[46:47], v[38:39]
	v_cvt_f32_u32_e32 v158, v158
	v_cvt_f32_u32_e32 v159, v159
	v_fmamk_f32 v158, v159, 0x4f800000, v158
	v_fmamk_f32 v36, v158, 0x26800000, v180
	v_mov_b32_e32 v244, v36
	v_cvt_pk_bf16_f32 v33, v38, v39
	v_rsq_f32_e32 v38, v36
	v_add_u32_e32 v173, 0x90, v168
	v_mad_i64_i32 v[36:37], s[56:57], v173, s69, v[112:113]
	v_lshl_add_u64 v[36:37], v[36:37], 0, v[114:115]
	v_cvt_pk_bf16_f32 v34, v40, v41
	v_cvt_pk_bf16_f32 v35, v42, v43
	global_store_dwordx4 v[36:37], v[32:35], off
	v_pk_mul_f32 v[24:25], v[24:25], v[16:17]
	v_pk_mul_f32 v[28:29], v[28:29], v[20:21]
	v_mul_f32_e32 v32, 0xbfb8aa3b, v38
	v_pk_mul_f32 v[16:17], v[16:17], v[32:33] op_sel_hi:[1,0]
	v_pk_mul_f32 v[20:21], v[20:21], v[32:33] op_sel_hi:[1,0]
	v_pk_mul_f32 v[26:27], v[26:27], v[18:19]
	v_exp_f32_e32 v16, v16
	v_exp_f32_e32 v17, v17
	v_pk_mul_f32 v[18:19], v[18:19], v[32:33] op_sel_hi:[1,0]
	v_exp_f32_e32 v20, v20
	v_exp_f32_e32 v21, v21
	v_exp_f32_e32 v18, v18
	v_exp_f32_e32 v19, v19
	v_pk_fma_f32 v[16:17], v[16:17], v[244:245], v[244:245] op_sel_hi:[1,0,0]
	v_pk_fma_f32 v[20:21], v[20:21], v[244:245], v[244:245] op_sel_hi:[1,0,0]
	v_pk_fma_f32 v[18:19], v[18:19], v[244:245], v[244:245] op_sel_hi:[1,0,0]
	v_pk_mul_f32 v[248:249], v[16:17], v[20:21]
	v_mul_f32_e32 v250, v248, v249
	v_rcp_f32_e32 v250, v250
	s_nop 0
	v_pk_mul_f32 v[248:249], v[248:249], v[250:251] op_sel:[1,0] op_sel_hi:[0,0]
	v_pk_mul_f32 v[252:253], v[248:249], v[16:17]
	v_pk_mul_f32 v[16:17], v[248:249], v[20:21]
	v_mul_f32_e32 v250, v18, v19
	v_rcp_f32_e32 v250, v250
	s_nop 0
	v_pk_mul_f32 v[18:19], v[18:19], v[250:251] op_sel:[1,0] op_sel_hi:[0,0]
	v_pk_mul_f32 v[24:25], v[24:25], v[16:17]
	v_pk_mul_f32 v[20:21], v[28:29], v[252:253]
	v_pk_mul_f32 v[26:27], v[26:27], v[18:19]
	v_pk_mul_f32 v[30:31], v[30:31], v[22:23]
	v_pk_mul_f32 v[22:23], v[22:23], v[32:33] op_sel_hi:[1,0]
	v_cvt_pk_bf16_f32 v16, v20, v21
	v_exp_f32_e32 v22, v22
	v_exp_f32_e32 v23, v23
	s_nop 0
	v_pk_fma_f32 v[22:23], v[22:23], v[244:245], v[244:245] op_sel_hi:[1,0,0]
	v_mul_f32_e32 v250, v22, v23
	v_rcp_f32_e32 v250, v250
	s_nop 0
	v_pk_mul_f32 v[22:23], v[22:23], v[250:251] op_sel:[1,0] op_sel_hi:[0,0]
	s_nop 0
	v_pk_mul_f32 v[22:23], v[30:31], v[22:23]
	v_cvt_f32_u32_e32 v156, v156
	v_cvt_f32_u32_e32 v157, v157
	v_fmamk_f32 v156, v157, 0x4f800000, v156
	v_fmamk_f32 v20, v156, 0x26800000, v180
	v_mov_b32_e32 v246, v20
	v_cvt_pk_bf16_f32 v17, v22, v23
	v_rsq_f32_e32 v22, v20
	v_add_u32_e32 v172, 0xa0, v168
	v_mad_i64_i32 v[20:21], s[56:57], v172, s69, v[112:113]
	v_lshl_add_u64 v[20:21], v[20:21], 0, v[114:115]
	v_cvt_pk_bf16_f32 v18, v24, v25
	v_cvt_pk_bf16_f32 v19, v26, v27
	global_store_dwordx4 v[20:21], v[16:19], off
	v_pk_mul_f32 v[12:13], v[12:13], v[4:5]
	v_pk_mul_f32 v[8:9], v[8:9], v[0:1]
	v_mul_f32_e32 v16, 0xbfb8aa3b, v22
	v_pk_mul_f32 v[4:5], v[4:5], v[16:17] op_sel_hi:[1,0]
	v_pk_mul_f32 v[0:1], v[0:1], v[16:17] op_sel_hi:[1,0]
	v_exp_f32_e32 v4, v4
	v_exp_f32_e32 v5, v5
	v_pk_mul_f32 v[10:11], v[10:11], v[2:3]
	v_exp_f32_e32 v0, v0
	v_exp_f32_e32 v1, v1
	v_pk_mul_f32 v[2:3], v[2:3], v[16:17] op_sel_hi:[1,0]
	v_pk_mul_f32 v[14:15], v[14:15], v[6:7]
	v_exp_f32_e32 v2, v2
	v_exp_f32_e32 v3, v3
	v_pk_mul_f32 v[6:7], v[6:7], v[16:17] op_sel_hi:[1,0]
	v_pk_fma_f32 v[4:5], v[4:5], v[246:247], v[246:247] op_sel_hi:[1,0,0]
	v_exp_f32_e32 v6, v6
	v_exp_f32_e32 v7, v7
	v_pk_fma_f32 v[0:1], v[0:1], v[246:247], v[246:247] op_sel_hi:[1,0,0]
	v_pk_mul_f32 v[248:249], v[4:5], v[0:1]
	v_mul_f32_e32 v250, v248, v249
	v_rcp_f32_e32 v250, v250
	s_nop 0
	v_pk_mul_f32 v[248:249], v[248:249], v[250:251] op_sel:[1,0] op_sel_hi:[0,0]
	v_pk_mul_f32 v[252:253], v[248:249], v[4:5]
	v_pk_mul_f32 v[4:5], v[248:249], v[0:1]
	v_pk_fma_f32 v[2:3], v[2:3], v[246:247], v[246:247] op_sel_hi:[1,0,0]
	v_pk_fma_f32 v[6:7], v[6:7], v[246:247], v[246:247] op_sel_hi:[1,0,0]
	v_pk_mul_f32 v[248:249], v[2:3], v[6:7]
	v_mul_f32_e32 v250, v248, v249
	v_rcp_f32_e32 v250, v250
	s_nop 0
	v_pk_mul_f32 v[248:249], v[248:249], v[250:251] op_sel:[1,0] op_sel_hi:[0,0]
	v_pk_mul_f32 v[254:255], v[248:249], v[2:3]
	v_pk_mul_f32 v[2:3], v[248:249], v[6:7]
	v_add_u32_e32 v169, 0xb0, v168
	v_pk_mul_f32 v[4:5], v[12:13], v[4:5]
	v_pk_mul_f32 v[8:9], v[8:9], v[252:253]
	v_pk_mul_f32 v[10:11], v[10:11], v[2:3]
	v_cvt_pk_bf16_f32 v0, v4, v5
	v_mad_i64_i32 v[4:5], s[56:57], v169, s69, v[112:113]
	v_lshl_add_u64 v[4:5], v[4:5], 0, v[114:115]
	s_and_b64 vcc, exec, s[2:3]
	s_mov_b64 s[2:3], -1
	v_pk_mul_f32 v[6:7], v[14:15], v[254:255]
	s_nop 0
	v_cvt_pk_bf16_f32 v1, v6, v7
	v_cvt_pk_bf16_f32 v2, v8, v9
	v_cvt_pk_bf16_f32 v3, v10, v11
	global_store_dwordx4 v[4:5], v[0:3], off
	s_cbranch_vccnz .LBB0_171
	s_nop 0
	v_or_b32_e32 v0, v155, v153
	v_or_b32_e32 v1, v154, v152
	v_or3_b32 v0, v0, v149, v151
	v_or3_b32 v1, v1, v148, v150
	v_or3_b32 v0, v0, v145, v147
	v_or3_b32 v1, v1, v144, v146
	s_andn2_b64 vcc, exec, s[4:5]
	v_or3_b32 v0, v0, v141, v143
	v_or3_b32 v1, v1, v140, v142
	s_cbranch_vccnz .LBB0_170
	s_barrier
	s_branch .LBB0_170

; __device__ __forceinline__ unsigned cvt_pk_bf16(float lo, float hi) { unsigned r; asm volatile("v_cvt_pk_bf16_f32 %0, %1, %2" : "=v"(r) : "v"(lo), "v"(hi)); return r; }
; __device__ __forceinline__ float ss_val(u64 v) { return (float)v * (1.0f / 1099511627776.0f); }
;     __device__ __forceinline__ void operator()(const f32x4 (&acc)[2][2][4][2], const Unit& u, const Unit& nxt, bool has_next, int wr, int wc, int fr, int fq) const {
;     ...
;         for (int g = 0; g < 8; ++g) cur[g] = rowss[row0 + (g >> 2) * HALF + (g & 3) * 16];
;         if (has_next) {
; #pragma unroll
;             for (int g = 0; g < 8; ++g) warm[g] = rowss[nxt.pm * BM + wr * 64 + fr + (g >> 2) * HALF + (g & 3) * 16];
;         }
; #pragma unroll
;         for (int g = 0; g < 8; ++g) {
;             const int ai = g >> 2, m = g & 3;
;             const float rs = __builtin_amdgcn_rsqf(ss_val(cur[g]) * inv_k + eps), rsn = rs * -1.44269504089f, rs2 = rs * rs;
;             float h[8];
; #pragma unroll
;             for (int n = 0; n < 2; ++n)
; #pragma unroll
;                 for (int jp = 0; jp < 2; ++jp) {
;                     const f32x2v av = {acc[ai][0][m][n][2 * jp], acc[ai][0][m][n][2 * jp + 1]}, gv = {acc[ai][1][m][n][2 * jp], acc[ai][1][m][n][2 * jp + 1]};
;                     const f32x2v t = (av * gv) * rs2, y = gv * rsn;
;                     f32x2v ex; ex.x = __builtin_amdgcn_exp2f(y.x); ex.y = __builtin_amdgcn_exp2f(y.y);
;                     const f32x2v d = ex + 1.0f;
;                     f32x2v r; r.x = __builtin_amdgcn_rcpf(d.x); r.y = __builtin_amdgcn_rcpf(d.y);
;                     const f32x2v o = t * r;
;                     h[4 * n + 2 * jp] = o.x; h[4 * n + 2 * jp + 1] = o.y;
;                 }
;             u32x4 w; w.x = cvt_pk_bf16(h[0], h[1]); w.y = cvt_pk_bf16(h[2], h[3]); w.z = cvt_pk_bf16(h[4], h[5]); w.w = cvt_pk_bf16(h[6], h[7]);
;             *(u32x4*)(O + (size_t)(row0 + ai * HALF + m * 16) * ldc + col0) = w;
;         }
.LBB0_665:
	s_waitcnt vmcnt(0)
	v_pk_mul_f32 v[124:125], v[124:125], v[116:117]
	v_pk_mul_f32 v[120:121], v[120:121], v[112:113]
	v_cvt_f32_u32_e32 v186, v186
	v_cvt_f32_u32_e32 v187, v187
	v_fmamk_f32 v186, v187, 0x4f800000, v186
	v_fmamk_f32 v161, v186, 0x26800000, v193
	v_mov_b32_e32 v232, v161
	v_rsq_f32_e32 v161, v161
	v_pk_mul_f32 v[126:127], v[126:127], v[118:119]
	v_pk_mul_f32 v[122:123], v[122:123], v[114:115]
	v_lshl_or_b32 v186, s86, 7, v189
	v_mul_f32_e32 v194, 0xbfb8aa3b, v161
	v_pk_mul_f32 v[116:117], v[116:117], v[194:195] op_sel_hi:[1,0]
	v_pk_mul_f32 v[112:113], v[112:113], v[194:195] op_sel_hi:[1,0]
	v_exp_f32_e32 v116, v116
	v_exp_f32_e32 v117, v117
	v_pk_mul_f32 v[118:119], v[118:119], v[194:195] op_sel_hi:[1,0]
	v_exp_f32_e32 v112, v112
	v_exp_f32_e32 v113, v113
	v_pk_mul_f32 v[114:115], v[114:115], v[194:195] op_sel_hi:[1,0]
	v_exp_f32_e32 v118, v118
	v_exp_f32_e32 v119, v119
	v_exp_f32_e32 v114, v114
	v_exp_f32_e32 v115, v115
	v_pk_fma_f32 v[116:117], v[116:117], v[232:233], v[232:233] op_sel_hi:[1,0,0]
	v_pk_fma_f32 v[112:113], v[112:113], v[232:233], v[232:233] op_sel_hi:[1,0,0]
	v_pk_fma_f32 v[118:119], v[118:119], v[232:233], v[232:233] op_sel_hi:[1,0,0]
	v_pk_mul_f32 v[248:249], v[116:117], v[112:113]
	v_mul_f32_e32 v250, v248, v249
	v_rcp_f32_e32 v250, v250
	s_nop 0
	v_pk_mul_f32 v[248:249], v[248:249], v[250:251] op_sel:[1,0] op_sel_hi:[0,0]
	v_pk_mul_f32 v[252:253], v[248:249], v[116:117]
	v_pk_mul_f32 v[116:117], v[248:249], v[112:113]
	v_pk_fma_f32 v[114:115], v[114:115], v[232:233], v[232:233] op_sel_hi:[1,0,0]
	v_pk_mul_f32 v[248:249], v[118:119], v[114:115]
	v_mul_f32_e32 v250, v248, v249
	v_rcp_f32_e32 v250, v250
	s_nop 0
	v_pk_mul_f32 v[248:249], v[248:249], v[250:251] op_sel:[1,0] op_sel_hi:[0,0]
	v_pk_mul_f32 v[254:255], v[248:249], v[118:119]
	v_pk_mul_f32 v[118:119], v[248:249], v[114:115]
	v_pk_mul_f32 v[116:117], v[124:125], v[116:117]
	v_pk_mul_f32 v[112:113], v[120:121], v[252:253]
	v_pk_mul_f32 v[118:119], v[126:127], v[118:119]
	v_pk_mul_f32 v[114:115], v[122:123], v[254:255]
	v_cvt_pk_bf16_f32 v116, v116, v117
	v_cvt_pk_bf16_f32 v117, v118, v119
	v_cvt_pk_bf16_f32 v118, v112, v113
	v_ashrrev_i32_e32 v187, 31, v186
	v_cvt_pk_bf16_f32 v119, v114, v115
	v_mov_b64_e32 v[112:113], s[24:25]
	v_mad_i64_i32 v[120:121], s[58:59], v182, s57, v[112:113]
	v_cvt_f32_u32_e32 v184, v184
	v_cvt_f32_u32_e32 v185, v185
	v_fmamk_f32 v184, v185, 0x4f800000, v184
	v_fmamk_f32 v114, v184, 0x26800000, v193
	v_mov_b32_e32 v234, v114
	v_rsq_f32_e32 v122, v114
	v_lshlrev_b64 v[114:115], 1, v[186:187]
	v_lshl_add_u64 v[120:121], v[120:121], 0, v[114:115]
	global_store_dwordx4 v[120:121], v[116:119], off
	v_pk_mul_f32 v[104:105], v[104:105], v[96:97]
	v_pk_mul_f32 v[108:109], v[108:109], v[100:101]
	v_mul_f32_e32 v116, 0xbfb8aa3b, v122
	v_pk_mul_f32 v[96:97], v[96:97], v[116:117] op_sel_hi:[1,0]
	v_pk_mul_f32 v[100:101], v[100:101], v[116:117] op_sel_hi:[1,0]
	v_pk_mul_f32 v[106:107], v[106:107], v[98:99]
	v_exp_f32_e32 v96, v96
	v_exp_f32_e32 v97, v97
	v_pk_mul_f32 v[98:99], v[98:99], v[116:117] op_sel_hi:[1,0]
	v_exp_f32_e32 v100, v100
	v_exp_f32_e32 v101, v101
	v_exp_f32_e32 v98, v98
	v_exp_f32_e32 v99, v99
	v_pk_fma_f32 v[96:97], v[96:97], v[234:235], v[234:235] op_sel_hi:[1,0,0]
	v_pk_fma_f32 v[100:101], v[100:101], v[234:235], v[234:235] op_sel_hi:[1,0,0]
	v_pk_fma_f32 v[98:99], v[98:99], v[234:235], v[234:235] op_sel_hi:[1,0,0]
	v_pk_mul_f32 v[248:249], v[96:97], v[100:101]
	v_mul_f32_e32 v250, v248, v249
	v_rcp_f32_e32 v250, v250
	s_nop 0
	v_pk_mul_f32 v[248:249], v[248:249], v[250:251] op_sel:[1,0] op_sel_hi:[0,0]
	v_pk_mul_f32 v[252:253], v[248:249], v[96:97]
	v_pk_mul_f32 v[96:97], v[248:249], v[100:101]
	v_mul_f32_e32 v250, v98, v99
	v_rcp_f32_e32 v250, v250
	s_nop 0
	v_pk_mul_f32 v[98:99], v[98:99], v[250:251] op_sel:[1,0] op_sel_hi:[0,0]
	v_pk_mul_f32 v[104:105], v[104:105], v[96:97]
	v_pk_mul_f32 v[100:101], v[108:109], v[252:253]
	v_pk_mul_f32 v[106:107], v[106:107], v[98:99]
	v_pk_mul_f32 v[110:111], v[110:111], v[102:103]
	v_pk_mul_f32 v[102:103], v[102:103], v[116:117] op_sel_hi:[1,0]
	v_cvt_pk_bf16_f32 v96, v100, v101
	v_exp_f32_e32 v102, v102
	v_exp_f32_e32 v103, v103
	s_nop 0
	v_pk_fma_f32 v[102:103], v[102:103], v[234:235], v[234:235] op_sel_hi:[1,0,0]
	v_mul_f32_e32 v250, v102, v103
	v_rcp_f32_e32 v250, v250
	s_nop 0
	v_pk_mul_f32 v[102:103], v[102:103], v[250:251] op_sel:[1,0] op_sel_hi:[0,0]
	s_nop 0
	v_pk_mul_f32 v[102:103], v[110:111], v[102:103]
	v_cvt_f32_u32_e32 v180, v180
	v_cvt_f32_u32_e32 v181, v181
	v_fmamk_f32 v180, v181, 0x4f800000, v180
	v_fmamk_f32 v100, v180, 0x26800000, v193
	v_mov_b32_e32 v236, v100
	v_cvt_pk_bf16_f32 v97, v102, v103
	v_rsq_f32_e32 v102, v100
	v_mad_i64_i32 v[100:101], s[58:59], v178, s57, v[112:113]
	v_lshl_add_u64 v[100:101], v[100:101], 0, v[114:115]
	v_cvt_pk_bf16_f32 v98, v104, v105
	v_cvt_pk_bf16_f32 v99, v106, v107
	global_store_dwordx4 v[100:101], v[96:99], off
	v_pk_mul_f32 v[88:89], v[88:89], v[80:81]
	v_pk_mul_f32 v[92:93], v[92:93], v[84:85]
	v_mul_f32_e32 v96, 0xbfb8aa3b, v102
	v_pk_mul_f32 v[80:81], v[80:81], v[96:97] op_sel_hi:[1,0]
	v_pk_mul_f32 v[84:85], v[84:85], v[96:97] op_sel_hi:[1,0]
	v_pk_mul_f32 v[90:91], v[90:91], v[82:83]
	v_exp_f32_e32 v80, v80
	v_exp_f32_e32 v81, v81
	v_pk_mul_f32 v[82:83], v[82:83], v[96:97] op_sel_hi:[1,0]
	v_exp_f32_e32 v84, v84
	v_exp_f32_e32 v85, v85
	v_exp_f32_e32 v82, v82
	v_exp_f32_e32 v83, v83
	v_pk_fma_f32 v[80:81], v[80:81], v[236:237], v[236:237] op_sel_hi:[1,0,0]
	v_pk_fma_f32 v[84:85], v[84:85], v[236:237], v[236:237] op_sel_hi:[1,0,0]
	v_pk_fma_f32 v[82:83], v[82:83], v[236:237], v[236:237] op_sel_hi:[1,0,0]
; __device__ __forceinline__ unsigned cvt_pk_bf16(float lo, float hi) { unsigned r; asm volatile("v_cvt_pk_bf16_f32 %0, %1, %2" : "=v"(r) : "v"(lo), "v"(hi)); return r; }
; __device__ __forceinline__ float ss_val(u64 v) { return (float)v * (1.0f / 1099511627776.0f); }
;     __device__ __forceinline__ void operator()(const f32x4 (&acc)[2][2][4][2], const Unit& u, const Unit& nxt, bool has_next, int wr, int wc, int fr, int fq) const {
;     ...
;         for (int g = 0; g < 8; ++g) {
;             const int ai = g >> 2, m = g & 3;
;             const float rs = __builtin_amdgcn_rsqf(ss_val(cur[g]) * inv_k + eps), rsn = rs * -1.44269504089f, rs2 = rs * rs;
;             float h[8];
; #pragma unroll
;             for (int n = 0; n < 2; ++n)
; #pragma unroll
;                 for (int jp = 0; jp < 2; ++jp) {
;                     const f32x2v av = {acc[ai][0][m][n][2 * jp], acc[ai][0][m][n][2 * jp + 1]}, gv = {acc[ai][1][m][n][2 * jp], acc[ai][1][m][n][2 * jp + 1]};
;                     const f32x2v t = (av * gv) * rs2, y = gv * rsn;
;                     f32x2v ex; ex.x = __builtin_amdgcn_exp2f(y.x); ex.y = __builtin_amdgcn_exp2f(y.y);
;                     const f32x2v d = ex + 1.0f;
;                     f32x2v r; r.x = __builtin_amdgcn_rcpf(d.x); r.y = __builtin_amdgcn_rcpf(d.y);
;                     const f32x2v o = t * r;
;                     h[4 * n + 2 * jp] = o.x; h[4 * n + 2 * jp + 1] = o.y;
;                 }
;             u32x4 w; w.x = cvt_pk_bf16(h[0], h[1]); w.y = cvt_pk_bf16(h[2], h[3]); w.z = cvt_pk_bf16(h[4], h[5]); w.w = cvt_pk_bf16(h[6], h[7]);
;             *(u32x4*)(O + (size_t)(row0 + ai * HALF + m * 16) * ldc + col0) = w;
;         }
	v_pk_mul_f32 v[248:249], v[80:81], v[84:85]
	v_mul_f32_e32 v250, v248, v249
	v_rcp_f32_e32 v250, v250
	s_nop 0
	v_pk_mul_f32 v[248:249], v[248:249], v[250:251] op_sel:[1,0] op_sel_hi:[0,0]
	v_pk_mul_f32 v[252:253], v[248:249], v[80:81]
	v_pk_mul_f32 v[80:81], v[248:249], v[84:85]
	v_mul_f32_e32 v250, v82, v83
	v_rcp_f32_e32 v250, v250
	s_nop 0
	v_pk_mul_f32 v[82:83], v[82:83], v[250:251] op_sel:[1,0] op_sel_hi:[0,0]
	v_pk_mul_f32 v[88:89], v[88:89], v[80:81]
	v_pk_mul_f32 v[84:85], v[92:93], v[252:253]
	v_pk_mul_f32 v[90:91], v[90:91], v[82:83]
	v_pk_mul_f32 v[94:95], v[94:95], v[86:87]
	v_pk_mul_f32 v[86:87], v[86:87], v[96:97] op_sel_hi:[1,0]
	v_cvt_pk_bf16_f32 v80, v84, v85
	v_exp_f32_e32 v86, v86
	v_exp_f32_e32 v87, v87
	s_nop 0
	v_pk_fma_f32 v[86:87], v[86:87], v[236:237], v[236:237] op_sel_hi:[1,0,0]
	v_mul_f32_e32 v250, v86, v87
	v_rcp_f32_e32 v250, v250
	s_nop 0
	v_pk_mul_f32 v[86:87], v[86:87], v[250:251] op_sel:[1,0] op_sel_hi:[0,0]
	s_nop 0
	v_pk_mul_f32 v[86:87], v[94:95], v[86:87]
	v_cvt_f32_u32_e32 v176, v176
	v_cvt_f32_u32_e32 v177, v177
	v_fmamk_f32 v176, v177, 0x4f800000, v176
	v_fmamk_f32 v84, v176, 0x26800000, v193
	v_mov_b32_e32 v238, v84
	v_cvt_pk_bf16_f32 v81, v86, v87
	v_rsq_f32_e32 v86, v84
	v_mad_i64_i32 v[84:85], s[58:59], v174, s57, v[112:113]
	v_lshl_add_u64 v[84:85], v[84:85], 0, v[114:115]
	v_cvt_pk_bf16_f32 v82, v88, v89
	v_cvt_pk_bf16_f32 v83, v90, v91
	global_store_dwordx4 v[84:85], v[80:83], off
	v_pk_mul_f32 v[72:73], v[72:73], v[64:65]
	v_pk_mul_f32 v[76:77], v[76:77], v[68:69]
	v_mul_f32_e32 v80, 0xbfb8aa3b, v86
	v_pk_mul_f32 v[64:65], v[64:65], v[80:81] op_sel_hi:[1,0]
	v_pk_mul_f32 v[68:69], v[68:69], v[80:81] op_sel_hi:[1,0]
	v_pk_mul_f32 v[74:75], v[74:75], v[66:67]
	v_exp_f32_e32 v64, v64
	v_exp_f32_e32 v65, v65
	v_pk_mul_f32 v[66:67], v[66:67], v[80:81] op_sel_hi:[1,0]
	v_exp_f32_e32 v68, v68
	v_exp_f32_e32 v69, v69
	v_exp_f32_e32 v66, v66
	v_exp_f32_e32 v67, v67
	v_pk_fma_f32 v[64:65], v[64:65], v[238:239], v[238:239] op_sel_hi:[1,0,0]
	v_pk_fma_f32 v[68:69], v[68:69], v[238:239], v[238:239] op_sel_hi:[1,0,0]
	v_pk_fma_f32 v[66:67], v[66:67], v[238:239], v[238:239] op_sel_hi:[1,0,0]
	v_pk_mul_f32 v[248:249], v[64:65], v[68:69]
	v_mul_f32_e32 v250, v248, v249
	v_rcp_f32_e32 v250, v250
	s_nop 0
	v_pk_mul_f32 v[248:249], v[248:249], v[250:251] op_sel:[1,0] op_sel_hi:[0,0]
	v_pk_mul_f32 v[252:253], v[248:249], v[64:65]
	v_pk_mul_f32 v[64:65], v[248:249], v[68:69]
	v_mul_f32_e32 v250, v66, v67
	v_rcp_f32_e32 v250, v250
	s_nop 0
	v_pk_mul_f32 v[66:67], v[66:67], v[250:251] op_sel:[1,0] op_sel_hi:[0,0]
	v_pk_mul_f32 v[72:73], v[72:73], v[64:65]
	v_pk_mul_f32 v[68:69], v[76:77], v[252:253]
	v_pk_mul_f32 v[74:75], v[74:75], v[66:67]
	v_pk_mul_f32 v[78:79], v[78:79], v[70:71]
	v_pk_mul_f32 v[70:71], v[70:71], v[80:81] op_sel_hi:[1,0]
	v_cvt_pk_bf16_f32 v64, v68, v69
	v_exp_f32_e32 v70, v70
	v_exp_f32_e32 v71, v71
	s_nop 0
	v_pk_fma_f32 v[70:71], v[70:71], v[238:239], v[238:239] op_sel_hi:[1,0,0]
	v_mul_f32_e32 v250, v70, v71
	v_rcp_f32_e32 v250, v250
	s_nop 0
	v_pk_mul_f32 v[70:71], v[70:71], v[250:251] op_sel:[1,0] op_sel_hi:[0,0]
	s_nop 0
	v_pk_mul_f32 v[70:71], v[78:79], v[70:71]
	v_cvt_f32_u32_e32 v172, v172
	v_cvt_f32_u32_e32 v173, v173
	v_fmamk_f32 v172, v173, 0x4f800000, v172
	v_fmamk_f32 v68, v172, 0x26800000, v193
	v_mov_b32_e32 v240, v68
	v_cvt_pk_bf16_f32 v65, v70, v71
	v_rsq_f32_e32 v70, v68
	v_mad_i64_i32 v[68:69], s[58:59], v170, s57, v[112:113]
	v_lshl_add_u64 v[68:69], v[68:69], 0, v[114:115]
	v_cvt_pk_bf16_f32 v66, v72, v73
	v_cvt_pk_bf16_f32 v67, v74, v75
	global_store_dwordx4 v[68:69], v[64:67], off
	v_pk_mul_f32 v[56:57], v[56:57], v[48:49]
	v_pk_mul_f32 v[60:61], v[60:61], v[52:53]
	v_mul_f32_e32 v64, 0xbfb8aa3b, v70
	v_pk_mul_f32 v[48:49], v[48:49], v[64:65] op_sel_hi:[1,0]
	v_pk_mul_f32 v[52:53], v[52:53], v[64:65] op_sel_hi:[1,0]
	v_pk_mul_f32 v[58:59], v[58:59], v[50:51]
	v_exp_f32_e32 v48, v48
	v_exp_f32_e32 v49, v49
	v_pk_mul_f32 v[50:51], v[50:51], v[64:65] op_sel_hi:[1,0]
	v_exp_f32_e32 v52, v52
	v_exp_f32_e32 v53, v53
	v_exp_f32_e32 v50, v50
	v_exp_f32_e32 v51, v51
	v_pk_fma_f32 v[48:49], v[48:49], v[240:241], v[240:241] op_sel_hi:[1,0,0]
	v_pk_fma_f32 v[52:53], v[52:53], v[240:241], v[240:241] op_sel_hi:[1,0,0]
	v_pk_fma_f32 v[50:51], v[50:51], v[240:241], v[240:241] op_sel_hi:[1,0,0]
	v_pk_mul_f32 v[248:249], v[48:49], v[52:53]
	v_mul_f32_e32 v250, v248, v249
	v_rcp_f32_e32 v250, v250
	s_nop 0
	v_pk_mul_f32 v[248:249], v[248:249], v[250:251] op_sel:[1,0] op_sel_hi:[0,0]
	v_pk_mul_f32 v[252:253], v[248:249], v[48:49]
	v_pk_mul_f32 v[48:49], v[248:249], v[52:53]
	v_mul_f32_e32 v250, v50, v51
	v_rcp_f32_e32 v250, v250
	s_nop 0
	v_pk_mul_f32 v[50:51], v[50:51], v[250:251] op_sel:[1,0] op_sel_hi:[0,0]
	v_pk_mul_f32 v[56:57], v[56:57], v[48:49]
	v_pk_mul_f32 v[52:53], v[60:61], v[252:253]
	v_pk_mul_f32 v[58:59], v[58:59], v[50:51]
	v_pk_mul_f32 v[62:63], v[62:63], v[54:55]
	v_pk_mul_f32 v[54:55], v[54:55], v[64:65] op_sel_hi:[1,0]
	v_cvt_pk_bf16_f32 v48, v52, v53
	v_exp_f32_e32 v54, v54
	v_exp_f32_e32 v55, v55
	s_nop 0
	v_pk_fma_f32 v[54:55], v[54:55], v[240:241], v[240:241] op_sel_hi:[1,0,0]
	v_mul_f32_e32 v250, v54, v55
	v_rcp_f32_e32 v250, v250
	s_nop 0
	v_pk_mul_f32 v[54:55], v[54:55], v[250:251] op_sel:[1,0] op_sel_hi:[0,0]
	s_nop 0
	v_pk_mul_f32 v[54:55], v[62:63], v[54:55]
	v_cvt_f32_u32_e32 v168, v168
	v_cvt_f32_u32_e32 v169, v169
	v_fmamk_f32 v168, v169, 0x4f800000, v168
	v_fmamk_f32 v52, v168, 0x26800000, v193
	v_mov_b32_e32 v242, v52
	v_cvt_pk_bf16_f32 v49, v54, v55
	v_rsq_f32_e32 v54, v52
	v_add_u32_e32 v141, 0x80, v182
	v_mad_i64_i32 v[52:53], s[58:59], v141, s57, v[112:113]
; __device__ __forceinline__ unsigned cvt_pk_bf16(float lo, float hi) { unsigned r; asm volatile("v_cvt_pk_bf16_f32 %0, %1, %2" : "=v"(r) : "v"(lo), "v"(hi)); return r; }
; __device__ __forceinline__ float ss_val(u64 v) { return (float)v * (1.0f / 1099511627776.0f); }
; #define PG8_BAR __builtin_amdgcn_s_barrier()
;     __device__ __forceinline__ void operator()(const f32x4 (&acc)[2][2][4][2], const Unit& u, const Unit& nxt, bool has_next, int wr, int wc, int fr, int fq) const {
;     ...
;         for (int g = 0; g < 8; ++g) {
;             const int ai = g >> 2, m = g & 3;
;             const float rs = __builtin_amdgcn_rsqf(ss_val(cur[g]) * inv_k + eps), rsn = rs * -1.44269504089f, rs2 = rs * rs;
;             float h[8];
; #pragma unroll
;             for (int n = 0; n < 2; ++n)
; #pragma unroll
;                 for (int jp = 0; jp < 2; ++jp) {
;                     const f32x2v av = {acc[ai][0][m][n][2 * jp], acc[ai][0][m][n][2 * jp + 1]}, gv = {acc[ai][1][m][n][2 * jp], acc[ai][1][m][n][2 * jp + 1]};
;                     const f32x2v t = (av * gv) * rs2, y = gv * rsn;
;                     f32x2v ex; ex.x = __builtin_amdgcn_exp2f(y.x); ex.y = __builtin_amdgcn_exp2f(y.y);
;                     const f32x2v d = ex + 1.0f;
;                     f32x2v r; r.x = __builtin_amdgcn_rcpf(d.x); r.y = __builtin_amdgcn_rcpf(d.y);
;                     const f32x2v o = t * r;
;                     h[4 * n + 2 * jp] = o.x; h[4 * n + 2 * jp + 1] = o.y;
;                 }
;             u32x4 w; w.x = cvt_pk_bf16(h[0], h[1]); w.y = cvt_pk_bf16(h[2], h[3]); w.z = cvt_pk_bf16(h[4], h[5]); w.w = cvt_pk_bf16(h[6], h[7]);
;             *(u32x4*)(O + (size_t)(row0 + ai * HALF + m * 16) * ldc + col0) = w;
;         }
;         if (has_next) { u64 x = 0;
; #pragma unroll
;             for (int g = 0; g < 8; ++g) x |= warm[g];
;             asm volatile("" :: "v"((unsigned)x), "v"((unsigned)(x >> 32))); }
; template <class Epi, class Sched, bool ALIGN_EPI = false, bool SP2 = false>
; __device__ __forceinline__ void gemm_phase(PG8_LAS unsigned char* lds, const Gemm g, const Sched& S, const Epi& E) {
;     ...
;         cur = nxt; cA = nA; cB = nB; ++ui;
;         if constexpr (ALIGN_EPI) { if (wr == 1) PG8_BAR; }
	v_lshl_add_u64 v[52:53], v[52:53], 0, v[114:115]
	v_cvt_pk_bf16_f32 v50, v56, v57
	v_cvt_pk_bf16_f32 v51, v58, v59
	global_store_dwordx4 v[52:53], v[48:51], off
	v_pk_mul_f32 v[40:41], v[40:41], v[32:33]
	v_pk_mul_f32 v[44:45], v[44:45], v[36:37]
	v_mul_f32_e32 v48, 0xbfb8aa3b, v54
	v_pk_mul_f32 v[32:33], v[32:33], v[48:49] op_sel_hi:[1,0]
	v_pk_mul_f32 v[36:37], v[36:37], v[48:49] op_sel_hi:[1,0]
	v_pk_mul_f32 v[42:43], v[42:43], v[34:35]
	v_exp_f32_e32 v32, v32
	v_exp_f32_e32 v33, v33
	v_pk_mul_f32 v[34:35], v[34:35], v[48:49] op_sel_hi:[1,0]
	v_exp_f32_e32 v36, v36
	v_exp_f32_e32 v37, v37
	v_exp_f32_e32 v34, v34
	v_exp_f32_e32 v35, v35
	v_pk_fma_f32 v[32:33], v[32:33], v[242:243], v[242:243] op_sel_hi:[1,0,0]
	v_pk_fma_f32 v[36:37], v[36:37], v[242:243], v[242:243] op_sel_hi:[1,0,0]
	v_pk_fma_f32 v[34:35], v[34:35], v[242:243], v[242:243] op_sel_hi:[1,0,0]
	v_pk_mul_f32 v[248:249], v[32:33], v[36:37]
	v_mul_f32_e32 v250, v248, v249
	v_rcp_f32_e32 v250, v250
	s_nop 0
	v_pk_mul_f32 v[248:249], v[248:249], v[250:251] op_sel:[1,0] op_sel_hi:[0,0]
	v_pk_mul_f32 v[252:253], v[248:249], v[32:33]
	v_pk_mul_f32 v[32:33], v[248:249], v[36:37]
	v_mul_f32_e32 v250, v34, v35
	v_rcp_f32_e32 v250, v250
	s_nop 0
	v_pk_mul_f32 v[34:35], v[34:35], v[250:251] op_sel:[1,0] op_sel_hi:[0,0]
	v_pk_mul_f32 v[40:41], v[40:41], v[32:33]
	v_pk_mul_f32 v[36:37], v[44:45], v[252:253]
	v_pk_mul_f32 v[42:43], v[42:43], v[34:35]
	v_pk_mul_f32 v[46:47], v[46:47], v[38:39]
	v_pk_mul_f32 v[38:39], v[38:39], v[48:49] op_sel_hi:[1,0]
	v_cvt_pk_bf16_f32 v32, v36, v37
	v_exp_f32_e32 v38, v38
	v_exp_f32_e32 v39, v39
	s_nop 0
	v_pk_fma_f32 v[38:39], v[38:39], v[242:243], v[242:243] op_sel_hi:[1,0,0]
	v_mul_f32_e32 v250, v38, v39
	v_rcp_f32_e32 v250, v250
	s_nop 0
	v_pk_mul_f32 v[38:39], v[38:39], v[250:251] op_sel:[1,0] op_sel_hi:[0,0]
	s_nop 0
	v_pk_mul_f32 v[38:39], v[46:47], v[38:39]
	v_cvt_f32_u32_e32 v166, v166
	v_cvt_f32_u32_e32 v167, v167
	v_fmamk_f32 v166, v167, 0x4f800000, v166
	v_fmamk_f32 v36, v166, 0x26800000, v193
	v_mov_b32_e32 v244, v36
	v_cvt_pk_bf16_f32 v33, v38, v39
	v_rsq_f32_e32 v38, v36
	v_mad_i64_i32 v[36:37], s[58:59], v164, s57, v[112:113]
	v_lshl_add_u64 v[36:37], v[36:37], 0, v[114:115]
	v_cvt_pk_bf16_f32 v34, v40, v41
	v_cvt_pk_bf16_f32 v35, v42, v43
	global_store_dwordx4 v[36:37], v[32:35], off
	v_pk_mul_f32 v[24:25], v[24:25], v[16:17]
	v_pk_mul_f32 v[28:29], v[28:29], v[20:21]
	v_mul_f32_e32 v32, 0xbfb8aa3b, v38
	v_pk_mul_f32 v[16:17], v[16:17], v[32:33] op_sel_hi:[1,0]
	v_pk_mul_f32 v[20:21], v[20:21], v[32:33] op_sel_hi:[1,0]
	v_pk_mul_f32 v[26:27], v[26:27], v[18:19]
	v_exp_f32_e32 v16, v16
	v_exp_f32_e32 v17, v17
	v_pk_mul_f32 v[18:19], v[18:19], v[32:33] op_sel_hi:[1,0]
	v_exp_f32_e32 v20, v20
	v_exp_f32_e32 v21, v21
	v_exp_f32_e32 v18, v18
	v_exp_f32_e32 v19, v19
	v_pk_fma_f32 v[16:17], v[16:17], v[244:245], v[244:245] op_sel_hi:[1,0,0]
	v_pk_fma_f32 v[20:21], v[20:21], v[244:245], v[244:245] op_sel_hi:[1,0,0]
	v_pk_fma_f32 v[18:19], v[18:19], v[244:245], v[244:245] op_sel_hi:[1,0,0]
	v_pk_mul_f32 v[248:249], v[16:17], v[20:21]
	v_mul_f32_e32 v250, v248, v249
	v_rcp_f32_e32 v250, v250
	s_nop 0
	v_pk_mul_f32 v[248:249], v[248:249], v[250:251] op_sel:[1,0] op_sel_hi:[0,0]
	v_pk_mul_f32 v[252:253], v[248:249], v[16:17]
	v_pk_mul_f32 v[16:17], v[248:249], v[20:21]
	v_mul_f32_e32 v250, v18, v19
	v_rcp_f32_e32 v250, v250
	s_nop 0
	v_pk_mul_f32 v[18:19], v[18:19], v[250:251] op_sel:[1,0] op_sel_hi:[0,0]
	v_pk_mul_f32 v[24:25], v[24:25], v[16:17]
	v_pk_mul_f32 v[20:21], v[28:29], v[252:253]
	v_pk_mul_f32 v[26:27], v[26:27], v[18:19]
	v_pk_mul_f32 v[30:31], v[30:31], v[22:23]
	v_pk_mul_f32 v[22:23], v[22:23], v[32:33] op_sel_hi:[1,0]
	v_cvt_pk_bf16_f32 v16, v20, v21
	v_exp_f32_e32 v22, v22
	v_exp_f32_e32 v23, v23
	s_nop 0
	v_pk_fma_f32 v[22:23], v[22:23], v[244:245], v[244:245] op_sel_hi:[1,0,0]
	v_mul_f32_e32 v250, v22, v23
	v_rcp_f32_e32 v250, v250
	s_nop 0
	v_pk_mul_f32 v[22:23], v[22:23], v[250:251] op_sel:[1,0] op_sel_hi:[0,0]
	s_nop 0
	v_pk_mul_f32 v[22:23], v[30:31], v[22:23]
	v_cvt_f32_u32_e32 v162, v162
	v_cvt_f32_u32_e32 v163, v163
	v_fmamk_f32 v162, v163, 0x4f800000, v162
	v_fmamk_f32 v20, v162, 0x26800000, v193
	v_mov_b32_e32 v246, v20
	v_cvt_pk_bf16_f32 v17, v22, v23
	v_rsq_f32_e32 v22, v20
	v_mad_i64_i32 v[20:21], s[58:59], v160, s57, v[112:113]
	v_lshl_add_u64 v[20:21], v[20:21], 0, v[114:115]
	v_cvt_pk_bf16_f32 v18, v24, v25
	v_cvt_pk_bf16_f32 v19, v26, v27
	global_store_dwordx4 v[20:21], v[16:19], off
	v_pk_mul_f32 v[12:13], v[12:13], v[4:5]
	v_pk_mul_f32 v[8:9], v[8:9], v[0:1]
	v_mul_f32_e32 v16, 0xbfb8aa3b, v22
	v_pk_mul_f32 v[4:5], v[4:5], v[16:17] op_sel_hi:[1,0]
	v_pk_mul_f32 v[0:1], v[0:1], v[16:17] op_sel_hi:[1,0]
	v_exp_f32_e32 v4, v4
	v_exp_f32_e32 v5, v5
	v_pk_mul_f32 v[10:11], v[10:11], v[2:3]
	v_exp_f32_e32 v0, v0
	v_exp_f32_e32 v1, v1
	v_pk_mul_f32 v[2:3], v[2:3], v[16:17] op_sel_hi:[1,0]
	v_pk_mul_f32 v[14:15], v[14:15], v[6:7]
	v_exp_f32_e32 v2, v2
	v_exp_f32_e32 v3, v3
	v_pk_mul_f32 v[6:7], v[6:7], v[16:17] op_sel_hi:[1,0]
	v_pk_fma_f32 v[4:5], v[4:5], v[246:247], v[246:247] op_sel_hi:[1,0,0]
	v_exp_f32_e32 v6, v6
	v_exp_f32_e32 v7, v7
	v_pk_fma_f32 v[0:1], v[0:1], v[246:247], v[246:247] op_sel_hi:[1,0,0]
	v_pk_mul_f32 v[248:249], v[4:5], v[0:1]
	v_mul_f32_e32 v250, v248, v249
	v_rcp_f32_e32 v250, v250
	s_nop 0
	v_pk_mul_f32 v[248:249], v[248:249], v[250:251] op_sel:[1,0] op_sel_hi:[0,0]
	v_pk_mul_f32 v[252:253], v[248:249], v[4:5]
	v_pk_mul_f32 v[4:5], v[248:249], v[0:1]
	v_pk_fma_f32 v[2:3], v[2:3], v[246:247], v[246:247] op_sel_hi:[1,0,0]
	v_pk_fma_f32 v[6:7], v[6:7], v[246:247], v[246:247] op_sel_hi:[1,0,0]
	v_pk_mul_f32 v[248:249], v[2:3], v[6:7]
	v_mul_f32_e32 v250, v248, v249
	v_rcp_f32_e32 v250, v250
	s_nop 0
	v_pk_mul_f32 v[248:249], v[248:249], v[250:251] op_sel:[1,0] op_sel_hi:[0,0]
	v_pk_mul_f32 v[254:255], v[248:249], v[2:3]
	v_pk_mul_f32 v[2:3], v[248:249], v[6:7]
	v_pk_mul_f32 v[4:5], v[12:13], v[4:5]
	v_pk_mul_f32 v[8:9], v[8:9], v[252:253]
	v_pk_mul_f32 v[10:11], v[10:11], v[2:3]
	v_cvt_pk_bf16_f32 v0, v4, v5
	v_mad_i64_i32 v[4:5], s[58:59], v140, s57, v[112:113]
	v_lshl_add_u64 v[4:5], v[4:5], 0, v[114:115]
	s_and_b64 vcc, exec, s[4:5]
	s_mov_b64 s[4:5], -1
	v_pk_mul_f32 v[6:7], v[14:15], v[254:255]
	s_nop 0
	v_cvt_pk_bf16_f32 v1, v6, v7
	v_cvt_pk_bf16_f32 v2, v8, v9
	v_cvt_pk_bf16_f32 v3, v10, v11
	global_store_dwordx4 v[4:5], v[0:3], off
	s_cbranch_vccnz .LBB0_656
	s_nop 0
	v_or_b32_e32 v0, v159, v157
	v_or_b32_e32 v1, v158, v156
	v_or3_b32 v0, v0, v153, v155
	v_or3_b32 v1, v1, v152, v154
	v_or3_b32 v0, v0, v149, v151
	v_or3_b32 v1, v1, v148, v150
	s_andn2_b64 vcc, exec, s[6:7]
	v_or3_b32 v0, v0, v143, v147
	v_or3_b32 v1, v1, v142, v146
	s_cbranch_vccnz .LBB0_655
	s_barrier
	s_branch .LBB0_655

; __device__ __forceinline__ unsigned cvt_pk_bf16(float lo, float hi) { unsigned r; asm volatile("v_cvt_pk_bf16_f32 %0, %1, %2" : "=v"(r) : "v"(lo), "v"(hi)); return r; }
; __device__ __forceinline__ float ss_val(u64 v) { return (float)v * (1.0f / 1099511627776.0f); }
;     __device__ __forceinline__ void operator()(const f32x4 (&acc)[2][2][4][2], const Unit& u, const Unit& nxt, bool has_next, int wr, int wc, int fr, int fq) const {
;     ...
;         for (int g = 0; g < 8; ++g) cur[g] = rowss[row0 + (g >> 2) * HALF + (g & 3) * 16];
;         if (has_next) {
; #pragma unroll
;             for (int g = 0; g < 8; ++g) warm[g] = rowss[nxt.pm * BM + wr * 64 + fr + (g >> 2) * HALF + (g & 3) * 16];
;         }
; #pragma unroll
;         for (int g = 0; g < 8; ++g) {
;             const int ai = g >> 2, m = g & 3;
;             const float rs = __builtin_amdgcn_rsqf(ss_val(cur[g]) * inv_k + eps), rsn = rs * -1.44269504089f, rs2 = rs * rs;
;             float h[8];
; #pragma unroll
;             for (int n = 0; n < 2; ++n)
; #pragma unroll
;                 for (int jp = 0; jp < 2; ++jp) {
;                     const f32x2v av = {acc[ai][0][m][n][2 * jp], acc[ai][0][m][n][2 * jp + 1]}, gv = {acc[ai][1][m][n][2 * jp], acc[ai][1][m][n][2 * jp + 1]};
;                     const f32x2v t = (av * gv) * rs2, y = gv * rsn;
;                     f32x2v ex; ex.x = __builtin_amdgcn_exp2f(y.x); ex.y = __builtin_amdgcn_exp2f(y.y);
;                     const f32x2v d = ex + 1.0f;
;                     f32x2v r; r.x = __builtin_amdgcn_rcpf(d.x); r.y = __builtin_amdgcn_rcpf(d.y);
;                     const f32x2v o = t * r;
;                     h[4 * n + 2 * jp] = o.x; h[4 * n + 2 * jp + 1] = o.y;
;                 }
;             u32x4 w; w.x = cvt_pk_bf16(h[0], h[1]); w.y = cvt_pk_bf16(h[2], h[3]); w.z = cvt_pk_bf16(h[4], h[5]); w.w = cvt_pk_bf16(h[6], h[7]);
;             *(u32x4*)(O + (size_t)(row0 + ai * HALF + m * 16) * ldc + col0) = w;
;         }
.LBB0_1298:
	s_waitcnt vmcnt(0)
	v_pk_mul_f32 v[124:125], v[124:125], v[116:117]
	v_pk_mul_f32 v[120:121], v[120:121], v[112:113]
	v_cvt_f32_u32_e32 v184, v184
	v_cvt_f32_u32_e32 v185, v185
	v_fmamk_f32 v184, v185, 0x4f800000, v184
	v_fmamk_f32 v159, v184, 0x26800000, v192
	v_mov_b32_e32 v232, v159
	v_rsq_f32_e32 v159, v159
	v_pk_mul_f32 v[126:127], v[126:127], v[118:119]
	v_pk_mul_f32 v[122:123], v[122:123], v[114:115]
	v_lshl_or_b32 v184, s62, 7, v188
	v_mul_f32_e32 v194, 0xbfb8aa3b, v159
	v_pk_mul_f32 v[116:117], v[116:117], v[194:195] op_sel_hi:[1,0]
	v_pk_mul_f32 v[112:113], v[112:113], v[194:195] op_sel_hi:[1,0]
	v_exp_f32_e32 v116, v116
	v_exp_f32_e32 v117, v117
	v_pk_mul_f32 v[118:119], v[118:119], v[194:195] op_sel_hi:[1,0]
	v_exp_f32_e32 v112, v112
	v_exp_f32_e32 v113, v113
	v_pk_mul_f32 v[114:115], v[114:115], v[194:195] op_sel_hi:[1,0]
	v_exp_f32_e32 v118, v118
	v_exp_f32_e32 v119, v119
	v_exp_f32_e32 v114, v114
	v_exp_f32_e32 v115, v115
	v_pk_fma_f32 v[116:117], v[116:117], v[232:233], v[232:233] op_sel_hi:[1,0,0]
	v_pk_fma_f32 v[112:113], v[112:113], v[232:233], v[232:233] op_sel_hi:[1,0,0]
	v_pk_fma_f32 v[118:119], v[118:119], v[232:233], v[232:233] op_sel_hi:[1,0,0]
	v_pk_mul_f32 v[248:249], v[116:117], v[112:113]
	v_mul_f32_e32 v250, v248, v249
	v_rcp_f32_e32 v250, v250
	s_nop 0
	v_pk_mul_f32 v[248:249], v[248:249], v[250:251] op_sel:[1,0] op_sel_hi:[0,0]
	v_pk_mul_f32 v[252:253], v[248:249], v[116:117]
	v_pk_mul_f32 v[116:117], v[248:249], v[112:113]
	v_pk_fma_f32 v[114:115], v[114:115], v[232:233], v[232:233] op_sel_hi:[1,0,0]
	v_pk_mul_f32 v[248:249], v[118:119], v[114:115]
	v_mul_f32_e32 v250, v248, v249
	v_rcp_f32_e32 v250, v250
	s_nop 0
	v_pk_mul_f32 v[248:249], v[248:249], v[250:251] op_sel:[1,0] op_sel_hi:[0,0]
	v_pk_mul_f32 v[254:255], v[248:249], v[118:119]
	v_pk_mul_f32 v[118:119], v[248:249], v[114:115]
	v_pk_mul_f32 v[116:117], v[124:125], v[116:117]
	v_pk_mul_f32 v[112:113], v[120:121], v[252:253]
	v_pk_mul_f32 v[118:119], v[126:127], v[118:119]
	v_pk_mul_f32 v[114:115], v[122:123], v[254:255]
	v_cvt_pk_bf16_f32 v116, v116, v117
	v_cvt_pk_bf16_f32 v117, v118, v119
	v_cvt_pk_bf16_f32 v118, v112, v113
	v_ashrrev_i32_e32 v185, 31, v184
	v_cvt_pk_bf16_f32 v119, v114, v115
	v_mov_b64_e32 v[112:113], s[24:25]
	v_mad_i64_i32 v[120:121], s[46:47], v180, s61, v[112:113]
	v_cvt_f32_u32_e32 v182, v182
	v_cvt_f32_u32_e32 v183, v183
	v_fmamk_f32 v182, v183, 0x4f800000, v182
	v_fmamk_f32 v114, v182, 0x26800000, v192
	v_mov_b32_e32 v234, v114
	v_rsq_f32_e32 v122, v114
	v_lshlrev_b64 v[114:115], 1, v[184:185]
	v_lshl_add_u64 v[120:121], v[120:121], 0, v[114:115]
	global_store_dwordx4 v[120:121], v[116:119], off
	v_pk_mul_f32 v[104:105], v[104:105], v[96:97]
	v_pk_mul_f32 v[108:109], v[108:109], v[100:101]
	v_mul_f32_e32 v116, 0xbfb8aa3b, v122
	v_pk_mul_f32 v[96:97], v[96:97], v[116:117] op_sel_hi:[1,0]
	v_pk_mul_f32 v[100:101], v[100:101], v[116:117] op_sel_hi:[1,0]
	v_pk_mul_f32 v[106:107], v[106:107], v[98:99]
	v_exp_f32_e32 v96, v96
	v_exp_f32_e32 v97, v97
	v_pk_mul_f32 v[98:99], v[98:99], v[116:117] op_sel_hi:[1,0]
	v_exp_f32_e32 v100, v100
	v_exp_f32_e32 v101, v101
	v_exp_f32_e32 v98, v98
	v_exp_f32_e32 v99, v99
	v_pk_fma_f32 v[96:97], v[96:97], v[234:235], v[234:235] op_sel_hi:[1,0,0]
	v_pk_fma_f32 v[100:101], v[100:101], v[234:235], v[234:235] op_sel_hi:[1,0,0]
	v_pk_fma_f32 v[98:99], v[98:99], v[234:235], v[234:235] op_sel_hi:[1,0,0]
	v_pk_mul_f32 v[248:249], v[96:97], v[100:101]
	v_mul_f32_e32 v250, v248, v249
	v_rcp_f32_e32 v250, v250
	s_nop 0
	v_pk_mul_f32 v[248:249], v[248:249], v[250:251] op_sel:[1,0] op_sel_hi:[0,0]
	v_pk_mul_f32 v[252:253], v[248:249], v[96:97]
	v_pk_mul_f32 v[96:97], v[248:249], v[100:101]
	v_mul_f32_e32 v250, v98, v99
	v_rcp_f32_e32 v250, v250
	s_nop 0
	v_pk_mul_f32 v[98:99], v[98:99], v[250:251] op_sel:[1,0] op_sel_hi:[0,0]
	v_pk_mul_f32 v[104:105], v[104:105], v[96:97]
	v_pk_mul_f32 v[100:101], v[108:109], v[252:253]
	v_pk_mul_f32 v[106:107], v[106:107], v[98:99]
	v_pk_mul_f32 v[110:111], v[110:111], v[102:103]
	v_pk_mul_f32 v[102:103], v[102:103], v[116:117] op_sel_hi:[1,0]
	v_cvt_pk_bf16_f32 v96, v100, v101
	v_exp_f32_e32 v102, v102
	v_exp_f32_e32 v103, v103
	s_nop 0
	v_pk_fma_f32 v[102:103], v[102:103], v[234:235], v[234:235] op_sel_hi:[1,0,0]
	v_mul_f32_e32 v250, v102, v103
	v_rcp_f32_e32 v250, v250
	s_nop 0
	v_pk_mul_f32 v[102:103], v[102:103], v[250:251] op_sel:[1,0] op_sel_hi:[0,0]
	s_nop 0
	v_pk_mul_f32 v[102:103], v[110:111], v[102:103]
	v_cvt_f32_u32_e32 v178, v178
	v_cvt_f32_u32_e32 v179, v179
	v_fmamk_f32 v178, v179, 0x4f800000, v178
	v_fmamk_f32 v100, v178, 0x26800000, v192
	v_mov_b32_e32 v236, v100
	v_cvt_pk_bf16_f32 v97, v102, v103
	v_rsq_f32_e32 v102, v100
	v_mad_i64_i32 v[100:101], s[46:47], v176, s61, v[112:113]
	v_lshl_add_u64 v[100:101], v[100:101], 0, v[114:115]
	v_cvt_pk_bf16_f32 v98, v104, v105
	v_cvt_pk_bf16_f32 v99, v106, v107
	global_store_dwordx4 v[100:101], v[96:99], off
	v_pk_mul_f32 v[88:89], v[88:89], v[80:81]
	v_pk_mul_f32 v[92:93], v[92:93], v[84:85]
	v_mul_f32_e32 v96, 0xbfb8aa3b, v102
	v_pk_mul_f32 v[80:81], v[80:81], v[96:97] op_sel_hi:[1,0]
	v_pk_mul_f32 v[84:85], v[84:85], v[96:97] op_sel_hi:[1,0]
	v_pk_mul_f32 v[90:91], v[90:91], v[82:83]
	v_exp_f32_e32 v80, v80
	v_exp_f32_e32 v81, v81
	v_pk_mul_f32 v[82:83], v[82:83], v[96:97] op_sel_hi:[1,0]
	v_exp_f32_e32 v84, v84
	v_exp_f32_e32 v85, v85
	v_exp_f32_e32 v82, v82
	v_exp_f32_e32 v83, v83
	v_pk_fma_f32 v[80:81], v[80:81], v[236:237], v[236:237] op_sel_hi:[1,0,0]
	v_pk_fma_f32 v[84:85], v[84:85], v[236:237], v[236:237] op_sel_hi:[1,0,0]
	v_pk_fma_f32 v[82:83], v[82:83], v[236:237], v[236:237] op_sel_hi:[1,0,0]
; __device__ __forceinline__ unsigned cvt_pk_bf16(float lo, float hi) { unsigned r; asm volatile("v_cvt_pk_bf16_f32 %0, %1, %2" : "=v"(r) : "v"(lo), "v"(hi)); return r; }
; __device__ __forceinline__ float ss_val(u64 v) { return (float)v * (1.0f / 1099511627776.0f); }
;     __device__ __forceinline__ void operator()(const f32x4 (&acc)[2][2][4][2], const Unit& u, const Unit& nxt, bool has_next, int wr, int wc, int fr, int fq) const {
;     ...
;         for (int g = 0; g < 8; ++g) {
;             const int ai = g >> 2, m = g & 3;
;             const float rs = __builtin_amdgcn_rsqf(ss_val(cur[g]) * inv_k + eps), rsn = rs * -1.44269504089f, rs2 = rs * rs;
;             float h[8];
; #pragma unroll
;             for (int n = 0; n < 2; ++n)
; #pragma unroll
;                 for (int jp = 0; jp < 2; ++jp) {
;                     const f32x2v av = {acc[ai][0][m][n][2 * jp], acc[ai][0][m][n][2 * jp + 1]}, gv = {acc[ai][1][m][n][2 * jp], acc[ai][1][m][n][2 * jp + 1]};
;                     const f32x2v t = (av * gv) * rs2, y = gv * rsn;
;                     f32x2v ex; ex.x = __builtin_amdgcn_exp2f(y.x); ex.y = __builtin_amdgcn_exp2f(y.y);
;                     const f32x2v d = ex + 1.0f;
;                     f32x2v r; r.x = __builtin_amdgcn_rcpf(d.x); r.y = __builtin_amdgcn_rcpf(d.y);
;                     const f32x2v o = t * r;
;                     h[4 * n + 2 * jp] = o.x; h[4 * n + 2 * jp + 1] = o.y;
;                 }
;             u32x4 w; w.x = cvt_pk_bf16(h[0], h[1]); w.y = cvt_pk_bf16(h[2], h[3]); w.z = cvt_pk_bf16(h[4], h[5]); w.w = cvt_pk_bf16(h[6], h[7]);
;             *(u32x4*)(O + (size_t)(row0 + ai * HALF + m * 16) * ldc + col0) = w;
;         }
	v_pk_mul_f32 v[248:249], v[80:81], v[84:85]
	v_mul_f32_e32 v250, v248, v249
	v_rcp_f32_e32 v250, v250
	s_nop 0
	v_pk_mul_f32 v[248:249], v[248:249], v[250:251] op_sel:[1,0] op_sel_hi:[0,0]
	v_pk_mul_f32 v[252:253], v[248:249], v[80:81]
	v_pk_mul_f32 v[80:81], v[248:249], v[84:85]
	v_mul_f32_e32 v250, v82, v83
	v_rcp_f32_e32 v250, v250
	s_nop 0
	v_pk_mul_f32 v[82:83], v[82:83], v[250:251] op_sel:[1,0] op_sel_hi:[0,0]
	v_pk_mul_f32 v[88:89], v[88:89], v[80:81]
	v_pk_mul_f32 v[84:85], v[92:93], v[252:253]
	v_pk_mul_f32 v[90:91], v[90:91], v[82:83]
	v_pk_mul_f32 v[94:95], v[94:95], v[86:87]
	v_pk_mul_f32 v[86:87], v[86:87], v[96:97] op_sel_hi:[1,0]
	v_cvt_pk_bf16_f32 v80, v84, v85
	v_exp_f32_e32 v86, v86
	v_exp_f32_e32 v87, v87
	s_nop 0
	v_pk_fma_f32 v[86:87], v[86:87], v[236:237], v[236:237] op_sel_hi:[1,0,0]
	v_mul_f32_e32 v250, v86, v87
	v_rcp_f32_e32 v250, v250
	s_nop 0
	v_pk_mul_f32 v[86:87], v[86:87], v[250:251] op_sel:[1,0] op_sel_hi:[0,0]
	s_nop 0
	v_pk_mul_f32 v[86:87], v[94:95], v[86:87]
	v_cvt_f32_u32_e32 v174, v174
	v_cvt_f32_u32_e32 v175, v175
	v_fmamk_f32 v174, v175, 0x4f800000, v174
	v_fmamk_f32 v84, v174, 0x26800000, v192
	v_mov_b32_e32 v238, v84
	v_cvt_pk_bf16_f32 v81, v86, v87
	v_rsq_f32_e32 v86, v84
	v_mad_i64_i32 v[84:85], s[46:47], v172, s61, v[112:113]
	v_lshl_add_u64 v[84:85], v[84:85], 0, v[114:115]
	v_cvt_pk_bf16_f32 v82, v88, v89
	v_cvt_pk_bf16_f32 v83, v90, v91
	global_store_dwordx4 v[84:85], v[80:83], off
	v_pk_mul_f32 v[72:73], v[72:73], v[64:65]
	v_pk_mul_f32 v[76:77], v[76:77], v[68:69]
	v_mul_f32_e32 v80, 0xbfb8aa3b, v86
	v_pk_mul_f32 v[64:65], v[64:65], v[80:81] op_sel_hi:[1,0]
	v_pk_mul_f32 v[68:69], v[68:69], v[80:81] op_sel_hi:[1,0]
	v_pk_mul_f32 v[74:75], v[74:75], v[66:67]
	v_exp_f32_e32 v64, v64
	v_exp_f32_e32 v65, v65
	v_pk_mul_f32 v[66:67], v[66:67], v[80:81] op_sel_hi:[1,0]
	v_exp_f32_e32 v68, v68
	v_exp_f32_e32 v69, v69
	v_exp_f32_e32 v66, v66
	v_exp_f32_e32 v67, v67
	v_pk_fma_f32 v[64:65], v[64:65], v[238:239], v[238:239] op_sel_hi:[1,0,0]
	v_pk_fma_f32 v[68:69], v[68:69], v[238:239], v[238:239] op_sel_hi:[1,0,0]
	v_pk_fma_f32 v[66:67], v[66:67], v[238:239], v[238:239] op_sel_hi:[1,0,0]
	v_pk_mul_f32 v[248:249], v[64:65], v[68:69]
	v_mul_f32_e32 v250, v248, v249
	v_rcp_f32_e32 v250, v250
	s_nop 0
	v_pk_mul_f32 v[248:249], v[248:249], v[250:251] op_sel:[1,0] op_sel_hi:[0,0]
	v_pk_mul_f32 v[252:253], v[248:249], v[64:65]
	v_pk_mul_f32 v[64:65], v[248:249], v[68:69]
	v_mul_f32_e32 v250, v66, v67
	v_rcp_f32_e32 v250, v250
	s_nop 0
	v_pk_mul_f32 v[66:67], v[66:67], v[250:251] op_sel:[1,0] op_sel_hi:[0,0]
	v_pk_mul_f32 v[72:73], v[72:73], v[64:65]
	v_pk_mul_f32 v[68:69], v[76:77], v[252:253]
	v_pk_mul_f32 v[74:75], v[74:75], v[66:67]
	v_pk_mul_f32 v[78:79], v[78:79], v[70:71]
	v_pk_mul_f32 v[70:71], v[70:71], v[80:81] op_sel_hi:[1,0]
	v_cvt_pk_bf16_f32 v64, v68, v69
	v_exp_f32_e32 v70, v70
	v_exp_f32_e32 v71, v71
	s_nop 0
	v_pk_fma_f32 v[70:71], v[70:71], v[238:239], v[238:239] op_sel_hi:[1,0,0]
	v_mul_f32_e32 v250, v70, v71
	v_rcp_f32_e32 v250, v250
	s_nop 0
	v_pk_mul_f32 v[70:71], v[70:71], v[250:251] op_sel:[1,0] op_sel_hi:[0,0]
	s_nop 0
	v_pk_mul_f32 v[70:71], v[78:79], v[70:71]
	v_cvt_f32_u32_e32 v170, v170
	v_cvt_f32_u32_e32 v171, v171
	v_fmamk_f32 v170, v171, 0x4f800000, v170
	v_fmamk_f32 v68, v170, 0x26800000, v192
	v_mov_b32_e32 v240, v68
	v_cvt_pk_bf16_f32 v65, v70, v71
	v_rsq_f32_e32 v70, v68
	v_mad_i64_i32 v[68:69], s[46:47], v168, s61, v[112:113]
	v_lshl_add_u64 v[68:69], v[68:69], 0, v[114:115]
	v_cvt_pk_bf16_f32 v66, v72, v73
	v_cvt_pk_bf16_f32 v67, v74, v75
	global_store_dwordx4 v[68:69], v[64:67], off
	v_pk_mul_f32 v[56:57], v[56:57], v[48:49]
	v_pk_mul_f32 v[60:61], v[60:61], v[52:53]
	v_mul_f32_e32 v64, 0xbfb8aa3b, v70
	v_pk_mul_f32 v[48:49], v[48:49], v[64:65] op_sel_hi:[1,0]
	v_pk_mul_f32 v[52:53], v[52:53], v[64:65] op_sel_hi:[1,0]
	v_pk_mul_f32 v[58:59], v[58:59], v[50:51]
	v_exp_f32_e32 v48, v48
	v_exp_f32_e32 v49, v49
	v_pk_mul_f32 v[50:51], v[50:51], v[64:65] op_sel_hi:[1,0]
	v_exp_f32_e32 v52, v52
	v_exp_f32_e32 v53, v53
	v_exp_f32_e32 v50, v50
	v_exp_f32_e32 v51, v51
	v_pk_fma_f32 v[48:49], v[48:49], v[240:241], v[240:241] op_sel_hi:[1,0,0]
	v_pk_fma_f32 v[52:53], v[52:53], v[240:241], v[240:241] op_sel_hi:[1,0,0]
	v_pk_fma_f32 v[50:51], v[50:51], v[240:241], v[240:241] op_sel_hi:[1,0,0]
	v_pk_mul_f32 v[248:249], v[48:49], v[52:53]
	v_mul_f32_e32 v250, v248, v249
	v_rcp_f32_e32 v250, v250
	s_nop 0
	v_pk_mul_f32 v[248:249], v[248:249], v[250:251] op_sel:[1,0] op_sel_hi:[0,0]
	v_pk_mul_f32 v[252:253], v[248:249], v[48:49]
	v_pk_mul_f32 v[48:49], v[248:249], v[52:53]
	v_mul_f32_e32 v250, v50, v51
	v_rcp_f32_e32 v250, v250
	s_nop 0
	v_pk_mul_f32 v[50:51], v[50:51], v[250:251] op_sel:[1,0] op_sel_hi:[0,0]
	v_pk_mul_f32 v[56:57], v[56:57], v[48:49]
	v_pk_mul_f32 v[52:53], v[60:61], v[252:253]
	v_pk_mul_f32 v[58:59], v[58:59], v[50:51]
	v_pk_mul_f32 v[62:63], v[62:63], v[54:55]
	v_pk_mul_f32 v[54:55], v[54:55], v[64:65] op_sel_hi:[1,0]
	v_cvt_pk_bf16_f32 v48, v52, v53
	v_exp_f32_e32 v54, v54
	v_exp_f32_e32 v55, v55
	s_nop 0
	v_pk_fma_f32 v[54:55], v[54:55], v[240:241], v[240:241] op_sel_hi:[1,0,0]
	v_mul_f32_e32 v250, v54, v55
	v_rcp_f32_e32 v250, v250
	s_nop 0
	v_pk_mul_f32 v[54:55], v[54:55], v[250:251] op_sel:[1,0] op_sel_hi:[0,0]
	s_nop 0
	v_pk_mul_f32 v[54:55], v[62:63], v[54:55]
	v_cvt_f32_u32_e32 v166, v166
	v_cvt_f32_u32_e32 v167, v167
	v_fmamk_f32 v166, v167, 0x4f800000, v166
	v_fmamk_f32 v52, v166, 0x26800000, v192
	v_mov_b32_e32 v242, v52
	v_cvt_pk_bf16_f32 v49, v54, v55
	v_rsq_f32_e32 v54, v52
	v_add_u32_e32 v141, 0x80, v180
	v_mad_i64_i32 v[52:53], s[46:47], v141, s61, v[112:113]
; __device__ __forceinline__ unsigned cvt_pk_bf16(float lo, float hi) { unsigned r; asm volatile("v_cvt_pk_bf16_f32 %0, %1, %2" : "=v"(r) : "v"(lo), "v"(hi)); return r; }
; __device__ __forceinline__ float ss_val(u64 v) { return (float)v * (1.0f / 1099511627776.0f); }
; #define PG8_BAR __builtin_amdgcn_s_barrier()
;     __device__ __forceinline__ void operator()(const f32x4 (&acc)[2][2][4][2], const Unit& u, const Unit& nxt, bool has_next, int wr, int wc, int fr, int fq) const {
;     ...
;         for (int g = 0; g < 8; ++g) {
;             const int ai = g >> 2, m = g & 3;
;             const float rs = __builtin_amdgcn_rsqf(ss_val(cur[g]) * inv_k + eps), rsn = rs * -1.44269504089f, rs2 = rs * rs;
;             float h[8];
; #pragma unroll
;             for (int n = 0; n < 2; ++n)
; #pragma unroll
;                 for (int jp = 0; jp < 2; ++jp) {
;                     const f32x2v av = {acc[ai][0][m][n][2 * jp], acc[ai][0][m][n][2 * jp + 1]}, gv = {acc[ai][1][m][n][2 * jp], acc[ai][1][m][n][2 * jp + 1]};
;                     const f32x2v t = (av * gv) * rs2, y = gv * rsn;
;                     f32x2v ex; ex.x = __builtin_amdgcn_exp2f(y.x); ex.y = __builtin_amdgcn_exp2f(y.y);
;                     const f32x2v d = ex + 1.0f;
;                     f32x2v r; r.x = __builtin_amdgcn_rcpf(d.x); r.y = __builtin_amdgcn_rcpf(d.y);
;                     const f32x2v o = t * r;
;                     h[4 * n + 2 * jp] = o.x; h[4 * n + 2 * jp + 1] = o.y;
;                 }
;             u32x4 w; w.x = cvt_pk_bf16(h[0], h[1]); w.y = cvt_pk_bf16(h[2], h[3]); w.z = cvt_pk_bf16(h[4], h[5]); w.w = cvt_pk_bf16(h[6], h[7]);
;             *(u32x4*)(O + (size_t)(row0 + ai * HALF + m * 16) * ldc + col0) = w;
;         }
;         if (has_next) { u64 x = 0;
; #pragma unroll
;             for (int g = 0; g < 8; ++g) x |= warm[g];
;             asm volatile("" :: "v"((unsigned)x), "v"((unsigned)(x >> 32))); }
; template <class Epi, class Sched, bool ALIGN_EPI = false, bool SP2 = false>
; __device__ __forceinline__ void gemm_phase(PG8_LAS unsigned char* lds, const Gemm g, const Sched& S, const Epi& E) {
;     ...
;         cur = nxt; cA = nA; cB = nB; ++ui;
;         if constexpr (ALIGN_EPI) { if (wr == 1) PG8_BAR; }
	v_lshl_add_u64 v[52:53], v[52:53], 0, v[114:115]
	v_cvt_pk_bf16_f32 v50, v56, v57
	v_cvt_pk_bf16_f32 v51, v58, v59
	global_store_dwordx4 v[52:53], v[48:51], off
	v_pk_mul_f32 v[40:41], v[40:41], v[32:33]
	v_pk_mul_f32 v[44:45], v[44:45], v[36:37]
	v_mul_f32_e32 v48, 0xbfb8aa3b, v54
	v_pk_mul_f32 v[32:33], v[32:33], v[48:49] op_sel_hi:[1,0]
	v_pk_mul_f32 v[36:37], v[36:37], v[48:49] op_sel_hi:[1,0]
	v_pk_mul_f32 v[42:43], v[42:43], v[34:35]
	v_exp_f32_e32 v32, v32
	v_exp_f32_e32 v33, v33
	v_pk_mul_f32 v[34:35], v[34:35], v[48:49] op_sel_hi:[1,0]
	v_exp_f32_e32 v36, v36
	v_exp_f32_e32 v37, v37
	v_exp_f32_e32 v34, v34
	v_exp_f32_e32 v35, v35
	v_pk_fma_f32 v[32:33], v[32:33], v[242:243], v[242:243] op_sel_hi:[1,0,0]
	v_pk_fma_f32 v[36:37], v[36:37], v[242:243], v[242:243] op_sel_hi:[1,0,0]
	v_pk_fma_f32 v[34:35], v[34:35], v[242:243], v[242:243] op_sel_hi:[1,0,0]
	v_pk_mul_f32 v[248:249], v[32:33], v[36:37]
	v_mul_f32_e32 v250, v248, v249
	v_rcp_f32_e32 v250, v250
	s_nop 0
	v_pk_mul_f32 v[248:249], v[248:249], v[250:251] op_sel:[1,0] op_sel_hi:[0,0]
	v_pk_mul_f32 v[252:253], v[248:249], v[32:33]
	v_pk_mul_f32 v[32:33], v[248:249], v[36:37]
	v_mul_f32_e32 v250, v34, v35
	v_rcp_f32_e32 v250, v250
	s_nop 0
	v_pk_mul_f32 v[34:35], v[34:35], v[250:251] op_sel:[1,0] op_sel_hi:[0,0]
	v_pk_mul_f32 v[40:41], v[40:41], v[32:33]
	v_pk_mul_f32 v[36:37], v[44:45], v[252:253]
	v_pk_mul_f32 v[42:43], v[42:43], v[34:35]
	v_pk_mul_f32 v[46:47], v[46:47], v[38:39]
	v_pk_mul_f32 v[38:39], v[38:39], v[48:49] op_sel_hi:[1,0]
	v_cvt_pk_bf16_f32 v32, v36, v37
	v_exp_f32_e32 v38, v38
	v_exp_f32_e32 v39, v39
	s_nop 0
	v_pk_fma_f32 v[38:39], v[38:39], v[242:243], v[242:243] op_sel_hi:[1,0,0]
	v_mul_f32_e32 v250, v38, v39
	v_rcp_f32_e32 v250, v250
	s_nop 0
	v_pk_mul_f32 v[38:39], v[38:39], v[250:251] op_sel:[1,0] op_sel_hi:[0,0]
	s_nop 0
	v_pk_mul_f32 v[38:39], v[46:47], v[38:39]
	v_cvt_f32_u32_e32 v164, v164
	v_cvt_f32_u32_e32 v165, v165
	v_fmamk_f32 v164, v165, 0x4f800000, v164
	v_fmamk_f32 v36, v164, 0x26800000, v192
	v_mov_b32_e32 v244, v36
	v_cvt_pk_bf16_f32 v33, v38, v39
	v_rsq_f32_e32 v38, v36
	v_mad_i64_i32 v[36:37], s[46:47], v162, s61, v[112:113]
	v_lshl_add_u64 v[36:37], v[36:37], 0, v[114:115]
	v_cvt_pk_bf16_f32 v34, v40, v41
	v_cvt_pk_bf16_f32 v35, v42, v43
	global_store_dwordx4 v[36:37], v[32:35], off
	v_pk_mul_f32 v[24:25], v[24:25], v[16:17]
	v_pk_mul_f32 v[28:29], v[28:29], v[20:21]
	v_mul_f32_e32 v32, 0xbfb8aa3b, v38
	v_pk_mul_f32 v[16:17], v[16:17], v[32:33] op_sel_hi:[1,0]
	v_pk_mul_f32 v[20:21], v[20:21], v[32:33] op_sel_hi:[1,0]
	v_pk_mul_f32 v[26:27], v[26:27], v[18:19]
	v_exp_f32_e32 v16, v16
	v_exp_f32_e32 v17, v17
	v_pk_mul_f32 v[18:19], v[18:19], v[32:33] op_sel_hi:[1,0]
	v_exp_f32_e32 v20, v20
	v_exp_f32_e32 v21, v21
	v_exp_f32_e32 v18, v18
	v_exp_f32_e32 v19, v19
	v_pk_fma_f32 v[16:17], v[16:17], v[244:245], v[244:245] op_sel_hi:[1,0,0]
	v_pk_fma_f32 v[20:21], v[20:21], v[244:245], v[244:245] op_sel_hi:[1,0,0]
	v_pk_fma_f32 v[18:19], v[18:19], v[244:245], v[244:245] op_sel_hi:[1,0,0]
	v_pk_mul_f32 v[248:249], v[16:17], v[20:21]
	v_mul_f32_e32 v250, v248, v249
	v_rcp_f32_e32 v250, v250
	s_nop 0
	v_pk_mul_f32 v[248:249], v[248:249], v[250:251] op_sel:[1,0] op_sel_hi:[0,0]
	v_pk_mul_f32 v[252:253], v[248:249], v[16:17]
	v_pk_mul_f32 v[16:17], v[248:249], v[20:21]
	v_mul_f32_e32 v250, v18, v19
	v_rcp_f32_e32 v250, v250
	s_nop 0
	v_pk_mul_f32 v[18:19], v[18:19], v[250:251] op_sel:[1,0] op_sel_hi:[0,0]
	v_pk_mul_f32 v[24:25], v[24:25], v[16:17]
	v_pk_mul_f32 v[20:21], v[28:29], v[252:253]
	v_pk_mul_f32 v[26:27], v[26:27], v[18:19]
	v_pk_mul_f32 v[30:31], v[30:31], v[22:23]
	v_pk_mul_f32 v[22:23], v[22:23], v[32:33] op_sel_hi:[1,0]
	v_cvt_pk_bf16_f32 v16, v20, v21
	v_exp_f32_e32 v22, v22
	v_exp_f32_e32 v23, v23
	s_nop 0
	v_pk_fma_f32 v[22:23], v[22:23], v[244:245], v[244:245] op_sel_hi:[1,0,0]
	v_mul_f32_e32 v250, v22, v23
	v_rcp_f32_e32 v250, v250
	s_nop 0
	v_pk_mul_f32 v[22:23], v[22:23], v[250:251] op_sel:[1,0] op_sel_hi:[0,0]
	s_nop 0
	v_pk_mul_f32 v[22:23], v[30:31], v[22:23]
	v_cvt_f32_u32_e32 v160, v160
	v_cvt_f32_u32_e32 v161, v161
	v_fmamk_f32 v160, v161, 0x4f800000, v160
	v_fmamk_f32 v20, v160, 0x26800000, v192
	v_mov_b32_e32 v246, v20
	v_cvt_pk_bf16_f32 v17, v22, v23
	v_rsq_f32_e32 v22, v20
	v_mad_i64_i32 v[20:21], s[46:47], v158, s61, v[112:113]
	v_lshl_add_u64 v[20:21], v[20:21], 0, v[114:115]
	v_cvt_pk_bf16_f32 v18, v24, v25
	v_cvt_pk_bf16_f32 v19, v26, v27
	global_store_dwordx4 v[20:21], v[16:19], off
	v_pk_mul_f32 v[12:13], v[12:13], v[4:5]
	v_pk_mul_f32 v[8:9], v[8:9], v[0:1]
	v_mul_f32_e32 v16, 0xbfb8aa3b, v22
	v_pk_mul_f32 v[4:5], v[4:5], v[16:17] op_sel_hi:[1,0]
	v_pk_mul_f32 v[0:1], v[0:1], v[16:17] op_sel_hi:[1,0]
	v_exp_f32_e32 v4, v4
	v_exp_f32_e32 v5, v5
	v_pk_mul_f32 v[10:11], v[10:11], v[2:3]
	v_exp_f32_e32 v0, v0
	v_exp_f32_e32 v1, v1
	v_pk_mul_f32 v[2:3], v[2:3], v[16:17] op_sel_hi:[1,0]
	v_pk_mul_f32 v[14:15], v[14:15], v[6:7]
	v_exp_f32_e32 v2, v2
	v_exp_f32_e32 v3, v3
	v_pk_mul_f32 v[6:7], v[6:7], v[16:17] op_sel_hi:[1,0]
	v_pk_fma_f32 v[4:5], v[4:5], v[246:247], v[246:247] op_sel_hi:[1,0,0]
	v_exp_f32_e32 v6, v6
	v_exp_f32_e32 v7, v7
	v_pk_fma_f32 v[0:1], v[0:1], v[246:247], v[246:247] op_sel_hi:[1,0,0]
	v_pk_mul_f32 v[248:249], v[4:5], v[0:1]
	v_mul_f32_e32 v250, v248, v249
	v_rcp_f32_e32 v250, v250
	s_nop 0
	v_pk_mul_f32 v[248:249], v[248:249], v[250:251] op_sel:[1,0] op_sel_hi:[0,0]
	v_pk_mul_f32 v[252:253], v[248:249], v[4:5]
	v_pk_mul_f32 v[4:5], v[248:249], v[0:1]
	v_pk_fma_f32 v[2:3], v[2:3], v[246:247], v[246:247] op_sel_hi:[1,0,0]
	v_pk_fma_f32 v[6:7], v[6:7], v[246:247], v[246:247] op_sel_hi:[1,0,0]
	v_pk_mul_f32 v[248:249], v[2:3], v[6:7]
	v_mul_f32_e32 v250, v248, v249
	v_rcp_f32_e32 v250, v250
	s_nop 0
	v_pk_mul_f32 v[248:249], v[248:249], v[250:251] op_sel:[1,0] op_sel_hi:[0,0]
	v_pk_mul_f32 v[254:255], v[248:249], v[2:3]
	v_pk_mul_f32 v[2:3], v[248:249], v[6:7]
	v_pk_mul_f32 v[4:5], v[12:13], v[4:5]
	v_pk_mul_f32 v[8:9], v[8:9], v[252:253]
	v_pk_mul_f32 v[10:11], v[10:11], v[2:3]
	v_cvt_pk_bf16_f32 v0, v4, v5
	v_mad_i64_i32 v[4:5], s[46:47], v140, s61, v[112:113]
	v_lshl_add_u64 v[4:5], v[4:5], 0, v[114:115]
	s_and_b64 vcc, exec, s[2:3]
	s_mov_b64 s[2:3], -1
	v_pk_mul_f32 v[6:7], v[14:15], v[254:255]
	s_nop 0
	v_cvt_pk_bf16_f32 v1, v6, v7
	v_cvt_pk_bf16_f32 v2, v8, v9
	v_cvt_pk_bf16_f32 v3, v10, v11
	global_store_dwordx4 v[4:5], v[0:3], off
	s_cbranch_vccnz .LBB0_1289
	s_nop 0
	v_or_b32_e32 v0, v157, v155
	v_or_b32_e32 v1, v156, v154
	v_or3_b32 v0, v0, v151, v153
	v_or3_b32 v1, v1, v150, v152
	v_or3_b32 v0, v0, v147, v149
	v_or3_b32 v1, v1, v146, v148
	s_andn2_b64 vcc, exec, s[4:5]
	v_or3_b32 v0, v0, v143, v145
	v_or3_b32 v1, v1, v142, v144
	s_cbranch_vccnz .LBB0_1288
	s_barrier
	s_branch .LBB0_1288

; __global__ void __launch_bounds__(NTHREADS, 2) fwd(Args a) {
	.amdhsa_kernel _Z3fwd4Args
		.amdhsa_group_segment_fixed_size 0
		.amdhsa_private_segment_fixed_size 0
		.amdhsa_kernarg_size 416
		.amdhsa_user_sgpr_count 2
		.amdhsa_user_sgpr_dispatch_ptr 0
		.amdhsa_user_sgpr_queue_ptr 0
		.amdhsa_user_sgpr_kernarg_segment_ptr 1
		.amdhsa_user_sgpr_dispatch_id 0
		.amdhsa_user_sgpr_kernarg_preload_length 0
		.amdhsa_user_sgpr_kernarg_preload_offset 0
		.amdhsa_user_sgpr_private_segment_size 0
		.amdhsa_uses_dynamic_stack 0
		.amdhsa_enable_private_segment 0
		.amdhsa_system_sgpr_workgroup_id_x 1
		.amdhsa_system_sgpr_workgroup_id_y 0
		.amdhsa_system_sgpr_workgroup_id_z 0
		.amdhsa_system_sgpr_workgroup_info 0
		.amdhsa_system_vgpr_workitem_id 2
		.amdhsa_next_free_vgpr 256
		.amdhsa_next_free_sgpr 102
		.amdhsa_accum_offset 256
		.amdhsa_reserve_vcc 1
		.amdhsa_float_round_mode_32 0
		.amdhsa_float_round_mode_16_64 0
		.amdhsa_float_denorm_mode_32 3
		.amdhsa_float_denorm_mode_16_64 3
		.amdhsa_dx10_clamp 1
		.amdhsa_ieee_mode 1
		.amdhsa_fp16_overflow 0
		.amdhsa_tg_split 0
		.amdhsa_exception_fp_ieee_invalid_op 0
		.amdhsa_exception_fp_denorm_src 0
		.amdhsa_exception_fp_ieee_div_zero 0
		.amdhsa_exception_fp_ieee_overflow 0
		.amdhsa_exception_fp_ieee_underflow 0
		.amdhsa_exception_fp_ieee_inexact 0
		.amdhsa_exception_int_div_zero 0
	.end_amdhsa_kernel

; __global__ void __launch_bounds__(NTHREADS, 2) fwd(Args a) {
amdhsa.kernels:
  - .agpr_count:     0
    .args:
      - .offset:         0
        .size:           160
        .value_kind:     by_value
      - .offset:         160
        .size:           4
        .value_kind:     hidden_block_count_x
      - .offset:         164
        .size:           4
        .value_kind:     hidden_block_count_y
      - .offset:         168
        .size:           4
        .value_kind:     hidden_block_count_z
      - .offset:         172
        .size:           2
        .value_kind:     hidden_group_size_x
      - .offset:         174
        .size:           2
        .value_kind:     hidden_group_size_y
      - .offset:         176
        .size:           2
        .value_kind:     hidden_group_size_z
      - .offset:         178
        .size:           2
        .value_kind:     hidden_remainder_x
      - .offset:         180
        .size:           2
        .value_kind:     hidden_remainder_y
      - .offset:         182
        .size:           2
        .value_kind:     hidden_remainder_z
      - .offset:         200
        .size:           8
        .value_kind:     hidden_global_offset_x
      - .offset:         208
        .size:           8
        .value_kind:     hidden_global_offset_y
      - .offset:         216
        .size:           8
        .value_kind:     hidden_global_offset_z
      - .offset:         224
        .size:           2
        .value_kind:     hidden_grid_dims
      - .offset:         248
        .size:           8
        .value_kind:     hidden_multigrid_sync_arg
      - .offset:         280
        .size:           4
        .value_kind:     hidden_dynamic_lds_size
    .group_segment_fixed_size: 0
    .kernarg_segment_align: 8
    .kernarg_segment_size: 416
    .language:       OpenCL C
    .language_version:
      - 2
      - 0
    .max_flat_workgroup_size: 512
    .name:           _Z3fwd4Args
    .private_segment_fixed_size: 0
    .sgpr_count:     108
    .sgpr_spill_count: 16
    .symbol:         _Z3fwd4Args.kd
    .uniform_work_group_size: 1
    .uses_dynamic_stack: false
    .vgpr_count:     256
    .vgpr_spill_count: 0
    .wavefront_size: 64
